# conv: two-stage row pipeline (front half of row r+1 interleaved with reduce/rsqrt/scale/store of row r); readlane-to-VALU pad fixed to 2 states
# speedup vs baseline: 1.0042x; 1.0002x over previous
; __device__ __forceinline__ float bf_lo(unsigned w) { return __uint_as_float(w << 16); }
; __device__ __forceinline__ float bf_hi(unsigned w) { return __uint_as_float(w & 0xffff0000u); }
; __global__ void __launch_bounds__(512, 2) trunk_fwd(Args args) {
;     ...
;             for (int ch = gw; ch < M / 16; ch += NGW) {
;                 const int r0 = ch * 16, t0 = r0 & (SEQ - 1), c0 = lane * 8;
;                 float w0[8], w1[8], w2[8], u1[8], u2[8];
; #pragma unroll
;                 for (int i = 0; i < 8; ++i) { w0[i] = cw[c0 + i]; w1[i] = cw[512 + c0 + i]; w2[i] = cw[1024 + c0 + i]; u1[i] = 0.f; u2[i] = 0.f; }
;                 if (t0 != 0) {
;                     const u32x4 c1 = *(const u32x4*)(Z + (size_t)(r0 - 1) * INP + 1280 + c0), c2 = *(const u32x4*)(Z + (size_t)(r0 - 2) * INP + 1280 + c0);
; #pragma unroll
;                     for (int i = 0; i < 4; ++i) { u1[2 * i] = bf_lo(c1[i]); u1[2 * i + 1] = bf_hi(c1[i]); u2[2 * i] = bf_lo(c2[i]); u2[2 * i + 1] = bf_hi(c2[i]); }
;                 }
;                 u32x4 gb_n = *(const u32x4*)(Z + (size_t)r0 * INP + 768 + c0), gu_n = *(const u32x4*)(Z + (size_t)r0 * INP + 1280 + c0);
;                 f32x4 pv_n = *(const f32x4*)(pl + (size_t)r0 * PLE + lane * 4);
; #pragma nounroll
;                 for (int rr = 0; rr < 16; ++rr) {
;                     const int r = r0 + rr;
;                     const u32x4 gb = gb_n, gu = gu_n; const f32x4 pv4 = pv_n;
;                     if (rr < 15) { gb_n = *(const u32x4*)(Z + (size_t)(r + 1) * INP + 768 + c0); gu_n = *(const u32x4*)(Z + (size_t)(r + 1) * INP + 1280 + c0);
;                                    pv_n = *(const f32x4*)(pl + (size_t)(r + 1) * PLE + lane * 4); }
;                     float cv[8], uu[8]; float ss = 0.f;
; #pragma unroll
;                     for (int i = 0; i < 4; ++i) {
;                         uu[2 * i] = bf_lo(gu[i]); uu[2 * i + 1] = bf_hi(gu[i]);
;                         cv[2 * i] = bf_lo(gb[i]) * (w0[2 * i] * uu[2 * i] + w1[2 * i] * u1[2 * i] + w2[2 * i] * u2[2 * i]);
;                         cv[2 * i + 1] = bf_hi(gb[i]) * (w0[2 * i + 1] * uu[2 * i + 1] + w1[2 * i + 1] * u1[2 * i + 1] + w2[2 * i + 1] * u2[2 * i + 1]);
;                     }
; #pragma unroll
;                     for (int i = 0; i < 8; ++i) { ss += cv[i] * cv[i]; u2[i] = u1[i]; u1[i] = uu[i]; }
;                     ss = wave_sum(ss);
.LBB0_1054:
	s_lshl_b32 s42, s40, 4
	s_mov_b32 s43, 0
	s_mov_b32 s41, s42
	global_load_dwordx4 v[164:167], v[54:55], off
	global_load_dwordx4 v[168:171], v[54:55], off offset:16
	global_load_dwordx4 v[172:175], v[54:55], off offset:2048
	global_load_dwordx4 v[176:179], v[54:55], off offset:2064
	global_load_dwordx4 v[180:183], v[56:57], off
	global_load_dwordx4 v[184:187], v[56:57], off offset:16
	s_and_b32 s0, s42, 0xfff
	s_cmp_lg_u32 s0, 0
	s_cselect_b32 s1, 1, 0
	s_sub_u32 s0, s42, s1
	v_mad_i64_i32 v[160:161], vcc, s0, v221, v[58:59]
	s_sub_u32 s0, s0, s1
	global_load_dwordx4 v[30:33], v[160:161], off offset:2560
	v_mad_i64_i32 v[160:161], vcc, s0, v221, v[58:59]
	global_load_dwordx4 v[26:29], v[160:161], off offset:2560
	s_lshl_b64 s[0:1], s[42:43], 11
	s_add_u32 s0, s0, 0x19500400
	s_addc_u32 s1, s1, 0
	s_add_u32 s0, s0, s38
	s_addc_u32 s1, s1, s39
	v_lshl_add_u64 v[156:157], s[0:1], 0, v[0:1]
	s_waitcnt vmcnt(0)
	v_lshlrev_b32_e32 v204, 16, v30
	v_and_b32_e32 v205, 0xffff0000, v30
	v_lshlrev_b32_e32 v206, 16, v31
	v_and_b32_e32 v207, 0xffff0000, v31
	v_lshlrev_b32_e32 v208, 16, v32
	v_and_b32_e32 v209, 0xffff0000, v32
	v_lshlrev_b32_e32 v210, 16, v33
	v_and_b32_e32 v211, 0xffff0000, v33
	v_lshlrev_b32_e32 v196, 16, v26
	v_and_b32_e32 v197, 0xffff0000, v26
	v_lshlrev_b32_e32 v198, 16, v27
	v_and_b32_e32 v199, 0xffff0000, v27
	v_lshlrev_b32_e32 v200, 16, v28
	v_and_b32_e32 v201, 0xffff0000, v28
	v_lshlrev_b32_e32 v202, 16, v29
	v_and_b32_e32 v203, 0xffff0000, v29
	s_and_b32 s0, s42, 0xfff
	s_cmp_lg_u32 s0, 0
	s_cbranch_scc1 .Lcv_taps_ok
	v_mov_b32_e32 v204, 0
	v_mov_b32_e32 v205, 0
	v_mov_b32_e32 v206, 0
	v_mov_b32_e32 v207, 0
	v_mov_b32_e32 v208, 0
	v_mov_b32_e32 v209, 0
	v_mov_b32_e32 v210, 0
	v_mov_b32_e32 v211, 0
	v_mov_b32_e32 v196, 0
	v_mov_b32_e32 v197, 0
	v_mov_b32_e32 v198, 0
	v_mov_b32_e32 v199, 0
	v_mov_b32_e32 v200, 0
	v_mov_b32_e32 v201, 0
	v_mov_b32_e32 v202, 0
	v_mov_b32_e32 v203, 0
.Lcv_taps_ok:
	v_mad_i64_i32 v[152:153], s[42:43], s41, v221, v[58:59]
	s_add_u32 s41, s41, 1
	global_load_dwordx4 v[2:5], v[152:153], off offset:1536
	global_load_dwordx4 v[18:21], v[152:153], off offset:2560
	v_mad_i64_i32 v[152:153], s[42:43], s41, v221, v[58:59]
	s_add_u32 s41, s41, 1
	global_load_dwordx4 v[6:9], v[152:153], off offset:1536
	global_load_dwordx4 v[22:25], v[152:153], off offset:2560
	v_mad_i64_i32 v[152:153], s[42:43], s41, v221, v[58:59]
	s_add_u32 s41, s41, 1
	global_load_dwordx4 v[10:13], v[152:153], off offset:1536
	global_load_dwordx4 v[26:29], v[152:153], off offset:2560
	v_mad_i64_i32 v[152:153], s[42:43], s41, v221, v[58:59]
	s_add_u32 s41, s41, 1
	global_load_dwordx4 v[14:17], v[152:153], off offset:1536
	global_load_dwordx4 v[30:33], v[152:153], off offset:2560
	s_waitcnt vmcnt(6)
	v_lshlrev_b32_e32 v188, 16, v18
	v_and_b32_e32 v189, 0xffff0000, v18
	v_lshlrev_b32_e32 v190, 16, v19
	v_and_b32_e32 v191, 0xffff0000, v19
	v_lshlrev_b32_e32 v192, 16, v20
	v_and_b32_e32 v193, 0xffff0000, v20
	v_lshlrev_b32_e32 v194, 16, v21
	v_and_b32_e32 v195, 0xffff0000, v21
	v_mul_f32_e32 v140, v164, v188
	v_mul_f32_e32 v141, v165, v189
	v_mul_f32_e32 v142, v166, v190
	v_mul_f32_e32 v143, v167, v191
	v_mul_f32_e32 v144, v168, v192
	v_mul_f32_e32 v145, v169, v193
	v_mul_f32_e32 v146, v170, v194
	v_mul_f32_e32 v147, v171, v195
	v_fmac_f32_e32 v140, v172, v204
	v_fmac_f32_e32 v141, v173, v205
	v_fmac_f32_e32 v142, v174, v206
	v_fmac_f32_e32 v143, v175, v207
	v_fmac_f32_e32 v144, v176, v208
	v_fmac_f32_e32 v145, v177, v209
	v_fmac_f32_e32 v146, v178, v210
	v_fmac_f32_e32 v147, v179, v211
	v_fmac_f32_e32 v140, v180, v196
	v_fmac_f32_e32 v141, v181, v197
	v_fmac_f32_e32 v142, v182, v198
	v_fmac_f32_e32 v143, v183, v199
	v_fmac_f32_e32 v144, v184, v200
	v_fmac_f32_e32 v145, v185, v201
	v_fmac_f32_e32 v146, v186, v202
	v_fmac_f32_e32 v147, v187, v203
	v_lshlrev_b32_e32 v150, 16, v2
	v_and_b32_e32 v151, 0xffff0000, v2
	v_mul_f32_e32 v140, v150, v140
	v_mul_f32_e32 v141, v151, v141
	v_lshlrev_b32_e32 v150, 16, v3
	v_and_b32_e32 v151, 0xffff0000, v3
	v_mul_f32_e32 v142, v150, v142
	v_mul_f32_e32 v143, v151, v143
	v_lshlrev_b32_e32 v150, 16, v4
	v_and_b32_e32 v151, 0xffff0000, v4
	v_mul_f32_e32 v144, v150, v144
	v_mul_f32_e32 v145, v151, v145
	v_lshlrev_b32_e32 v150, 16, v5
	v_and_b32_e32 v151, 0xffff0000, v5
	v_mul_f32_e32 v146, v150, v146
	v_mul_f32_e32 v147, v151, v147
	v_mul_f32_e32 v148, v140, v140
	v_fmac_f32_e32 v148, v141, v141
	v_fmac_f32_e32 v148, v142, v142
	v_fmac_f32_e32 v148, v143, v143
	v_fmac_f32_e32 v148, v144, v144
	v_fmac_f32_e32 v148, v145, v145
	v_fmac_f32_e32 v148, v146, v146
	v_fmac_f32_e32 v148, v147, v147
	v_mad_i64_i32 v[152:153], s[42:43], s41, v221, v[58:59]
	s_add_u32 s41, s41, 1
	global_load_dwordx4 v[2:5], v[152:153], off offset:1536
	global_load_dwordx4 v[18:21], v[152:153], off offset:2560
	s_nop 1
	v_add_f32_dpp v148, v148, v148 quad_perm:[1,0,3,2] row_mask:0xf bank_mask:0xf
	s_waitcnt vmcnt(6)
; __device__ __forceinline__ unsigned cvt_pk_bf16(float lo, float hi) { unsigned r; asm volatile("v_cvt_pk_bf16_f32 %0, %1, %2" : "=v"(r) : "v"(lo), "v"(hi)); return r; }
; __device__ __forceinline__ float bf_lo(unsigned w) { return __uint_as_float(w << 16); }
; __device__ __forceinline__ float bf_hi(unsigned w) { return __uint_as_float(w & 0xffff0000u); }
; __global__ void __launch_bounds__(512, 2) trunk_fwd(Args args) {
;     ...
;                 for (int rr = 0; rr < 16; ++rr) {
;                     const int r = r0 + rr;
;                     const u32x4 gb = gb_n, gu = gu_n; const f32x4 pv4 = pv_n;
;                     if (rr < 15) { gb_n = *(const u32x4*)(Z + (size_t)(r + 1) * INP + 768 + c0); gu_n = *(const u32x4*)(Z + (size_t)(r + 1) * INP + 1280 + c0);
;                                    pv_n = *(const f32x4*)(pl + (size_t)(r + 1) * PLE + lane * 4); }
;                     float cv[8], uu[8]; float ss = 0.f;
; #pragma unroll
;                     for (int i = 0; i < 4; ++i) {
;                         uu[2 * i] = bf_lo(gu[i]); uu[2 * i + 1] = bf_hi(gu[i]);
;                         cv[2 * i] = bf_lo(gb[i]) * (w0[2 * i] * uu[2 * i] + w1[2 * i] * u1[2 * i] + w2[2 * i] * u2[2 * i]);
;                         cv[2 * i + 1] = bf_hi(gb[i]) * (w0[2 * i + 1] * uu[2 * i + 1] + w1[2 * i + 1] * u1[2 * i + 1] + w2[2 * i + 1] * u2[2 * i + 1]);
;                     }
; #pragma unroll
;                     for (int i = 0; i < 8; ++i) { ss += cv[i] * cv[i]; u2[i] = u1[i]; u1[i] = uu[i]; }
;                     ss = wave_sum(ss);
;                     const float rc = rsqrtf(ss * (1.0f / 512.0f) + EPS);
;                     u32x4 oc;
; #pragma unroll
;                     for (int i = 0; i < 4; ++i) oc[i] = cvt_pk_bf16(cv[2 * i] * rc, cv[2 * i + 1] * rc);
;                     *(u32x4*)(MIX + (size_t)r * 1024 + 512 + c0) = oc;
;                     u32x2 pw; pw.x = cvt_pk_bf16(pv4[0], pv4[1]); pw.y = cvt_pk_bf16(pv4[2], pv4[3]);
;                     *(u32x2*)(PB + (size_t)r * PLE + lane * 4) = pw;
;                 }
	v_lshlrev_b32_e32 v196, 16, v22
	v_and_b32_e32 v197, 0xffff0000, v22
	v_add_f32_dpp v148, v148, v148 quad_perm:[2,3,0,1] row_mask:0xf bank_mask:0xf
	v_lshlrev_b32_e32 v198, 16, v23
	v_and_b32_e32 v199, 0xffff0000, v23
	v_lshlrev_b32_e32 v200, 16, v24
	v_add_f32_dpp v148, v148, v148 row_half_mirror row_mask:0xf bank_mask:0xf
	v_and_b32_e32 v201, 0xffff0000, v24
	v_lshlrev_b32_e32 v202, 16, v25
	v_add_f32_dpp v148, v148, v148 row_mirror row_mask:0xf bank_mask:0xf
	v_and_b32_e32 v203, 0xffff0000, v25
	v_mul_f32_e32 v34, v164, v196
	v_add_f32_dpp v148, v148, v148 row_bcast:15 row_mask:0xa bank_mask:0xf
	v_mul_f32_e32 v35, v165, v197
	v_mul_f32_e32 v36, v166, v198
	v_add_f32_dpp v148, v148, v148 row_bcast:31 row_mask:0xc bank_mask:0xf
	v_mul_f32_e32 v37, v167, v199
	v_mul_f32_e32 v38, v168, v200
	v_readlane_b32 s0, v148, 63
	v_mul_f32_e32 v39, v169, v201
	v_mul_f32_e32 v40, v170, v202
	v_mov_b32_e32 v148, s0
	v_mul_f32_e32 v41, v171, v203
	v_fmac_f32_e32 v34, v172, v188
	v_fmamk_f32 v148, v148, 0x3b000000, v162
	v_fmac_f32_e32 v35, v173, v189
	v_fmac_f32_e32 v36, v174, v190
	v_mul_f32_e32 v43, 0x4b800000, v148
	v_fmac_f32_e32 v37, v175, v191
	v_fmac_f32_e32 v38, v176, v192
	v_cmp_gt_f32_e32 vcc, s31, v148
	v_fmac_f32_e32 v39, v177, v193
	v_fmac_f32_e32 v40, v178, v194
	v_cndmask_b32_e32 v148, v148, v43, vcc
	v_fmac_f32_e32 v41, v179, v195
	v_fmac_f32_e32 v34, v180, v204
	v_rsq_f32_e32 v148, v148
	v_fmac_f32_e32 v35, v181, v205
	v_fmac_f32_e32 v36, v182, v206
	v_mul_f32_e32 v43, 0x45800000, v148
	v_fmac_f32_e32 v37, v183, v207
	v_fmac_f32_e32 v38, v184, v208
	v_cndmask_b32_e32 v149, v148, v43, vcc
	v_fmac_f32_e32 v39, v185, v209
	v_fmac_f32_e32 v40, v186, v210
	v_mul_f32_e32 v140, v149, v140
	v_fmac_f32_e32 v41, v187, v211
	v_lshlrev_b32_e32 v150, 16, v6
	v_mul_f32_e32 v141, v149, v141
	v_and_b32_e32 v151, 0xffff0000, v6
	v_mul_f32_e32 v34, v150, v34
	v_mul_f32_e32 v142, v149, v142
	v_mul_f32_e32 v35, v151, v35
	v_lshlrev_b32_e32 v150, 16, v7
	v_mul_f32_e32 v143, v149, v143
	v_and_b32_e32 v151, 0xffff0000, v7
	v_mul_f32_e32 v36, v150, v36
	v_mul_f32_e32 v144, v149, v144
	v_mul_f32_e32 v37, v151, v37
	v_lshlrev_b32_e32 v150, 16, v8
	v_mul_f32_e32 v145, v149, v145
	v_and_b32_e32 v151, 0xffff0000, v8
	v_mul_f32_e32 v38, v150, v38
	v_mul_f32_e32 v146, v149, v146
	v_mul_f32_e32 v39, v151, v39
	v_lshlrev_b32_e32 v150, 16, v9
	v_mul_f32_e32 v147, v149, v147
	v_and_b32_e32 v151, 0xffff0000, v9
	v_mul_f32_e32 v40, v150, v40
	v_cvt_pk_bf16_f32 v140, v140, v141
	v_mul_f32_e32 v41, v151, v41
	v_mul_f32_e32 v42, v34, v34
	v_cvt_pk_bf16_f32 v141, v142, v143
	v_fmac_f32_e32 v42, v35, v35
	v_fmac_f32_e32 v42, v36, v36
	v_cvt_pk_bf16_f32 v142, v144, v145
	v_fmac_f32_e32 v42, v37, v37
	v_fmac_f32_e32 v42, v38, v38
	v_cvt_pk_bf16_f32 v143, v146, v147
	v_fmac_f32_e32 v42, v39, v39
	v_fmac_f32_e32 v42, v40, v40
	global_store_dwordx4 v[156:157], v[140:143], off
	v_fmac_f32_e32 v42, v41, v41
	v_mad_i64_i32 v[152:153], s[42:43], s41, v221, v[58:59]
	s_add_u32 s41, s41, 1
	global_load_dwordx4 v[6:9], v[152:153], off offset:1536
	global_load_dwordx4 v[22:25], v[152:153], off offset:2560
	s_nop 1
	v_add_f32_dpp v42, v42, v42 quad_perm:[1,0,3,2] row_mask:0xf bank_mask:0xf
	s_waitcnt vmcnt(7)
	v_lshlrev_b32_e32 v204, 16, v26
	v_and_b32_e32 v205, 0xffff0000, v26
	v_add_f32_dpp v42, v42, v42 quad_perm:[2,3,0,1] row_mask:0xf bank_mask:0xf
	v_lshlrev_b32_e32 v206, 16, v27
	v_and_b32_e32 v207, 0xffff0000, v27
	v_add_f32_dpp v42, v42, v42 row_half_mirror row_mask:0xf bank_mask:0xf
	v_lshlrev_b32_e32 v208, 16, v28
	v_and_b32_e32 v209, 0xffff0000, v28
	v_add_f32_dpp v42, v42, v42 row_mirror row_mask:0xf bank_mask:0xf
	v_lshlrev_b32_e32 v210, 16, v29
	v_and_b32_e32 v211, 0xffff0000, v29
	v_add_f32_dpp v42, v42, v42 row_bcast:15 row_mask:0xa bank_mask:0xf
	v_mul_f32_e32 v140, v164, v204
	v_mul_f32_e32 v141, v165, v205
	v_add_f32_dpp v42, v42, v42 row_bcast:31 row_mask:0xc bank_mask:0xf
	v_mul_f32_e32 v142, v166, v206
	v_mul_f32_e32 v143, v167, v207
	v_readlane_b32 s0, v42, 63
	v_mul_f32_e32 v144, v168, v208
	v_mul_f32_e32 v145, v169, v209
	v_mov_b32_e32 v42, s0
	v_mul_f32_e32 v146, v170, v210
	v_mul_f32_e32 v147, v171, v211
	v_fmamk_f32 v42, v42, 0x3b000000, v162
	v_fmac_f32_e32 v140, v172, v196
	v_fmac_f32_e32 v141, v173, v197
	v_mul_f32_e32 v43, 0x4b800000, v42
	v_fmac_f32_e32 v142, v174, v198
	v_fmac_f32_e32 v143, v175, v199
	v_cmp_gt_f32_e32 vcc, s31, v42
	v_fmac_f32_e32 v144, v176, v200
	v_fmac_f32_e32 v145, v177, v201
	v_cndmask_b32_e32 v42, v42, v43, vcc
	v_fmac_f32_e32 v146, v178, v202
	v_fmac_f32_e32 v147, v179, v203
	v_rsq_f32_e32 v42, v42
	v_fmac_f32_e32 v140, v180, v188
	v_fmac_f32_e32 v141, v181, v189
	v_mul_f32_e32 v43, 0x45800000, v42
	v_fmac_f32_e32 v142, v182, v190
	v_fmac_f32_e32 v143, v183, v191
	v_cndmask_b32_e32 v149, v42, v43, vcc
	v_fmac_f32_e32 v144, v184, v192
	v_fmac_f32_e32 v145, v185, v193
	v_mul_f32_e32 v34, v149, v34
	v_fmac_f32_e32 v146, v186, v194
	v_fmac_f32_e32 v147, v187, v195
	v_mul_f32_e32 v35, v149, v35
	v_lshlrev_b32_e32 v150, 16, v10
	v_and_b32_e32 v151, 0xffff0000, v10
	v_mul_f32_e32 v36, v149, v36
	v_mul_f32_e32 v140, v150, v140
	v_mul_f32_e32 v141, v151, v141
	v_mul_f32_e32 v37, v149, v37
	v_lshlrev_b32_e32 v150, 16, v11
	v_and_b32_e32 v151, 0xffff0000, v11
	v_mul_f32_e32 v38, v149, v38
	v_mul_f32_e32 v142, v150, v142
	v_mul_f32_e32 v143, v151, v143
	v_mul_f32_e32 v39, v149, v39
	v_lshlrev_b32_e32 v150, 16, v12
	v_and_b32_e32 v151, 0xffff0000, v12
	v_mul_f32_e32 v40, v149, v40
	v_mul_f32_e32 v144, v150, v144
	v_mul_f32_e32 v145, v151, v145
	v_mul_f32_e32 v41, v149, v41
	v_lshlrev_b32_e32 v150, 16, v13
	v_and_b32_e32 v151, 0xffff0000, v13
	v_cvt_pk_bf16_f32 v34, v34, v35
	v_mul_f32_e32 v146, v150, v146
	v_mul_f32_e32 v147, v151, v147
	v_cvt_pk_bf16_f32 v35, v36, v37
	v_mul_f32_e32 v148, v140, v140
	v_fmac_f32_e32 v148, v141, v141
	v_cvt_pk_bf16_f32 v36, v38, v39
	v_fmac_f32_e32 v148, v142, v142
	v_fmac_f32_e32 v148, v143, v143
	v_cvt_pk_bf16_f32 v37, v40, v41
	v_fmac_f32_e32 v148, v144, v144
	v_fmac_f32_e32 v148, v145, v145
	global_store_dwordx4 v[156:157], v[34:37], off offset:2048
	v_fmac_f32_e32 v148, v146, v146
	v_fmac_f32_e32 v148, v147, v147
	v_lshl_add_u64 v[156:157], v[156:157], 0, s[20:21]
	v_mad_i64_i32 v[152:153], s[42:43], s41, v221, v[58:59]
	s_add_u32 s41, s41, 1
	global_load_dwordx4 v[10:13], v[152:153], off offset:1536
	global_load_dwordx4 v[26:29], v[152:153], off offset:2560
	s_nop 1
	v_add_f32_dpp v148, v148, v148 quad_perm:[1,0,3,2] row_mask:0xf bank_mask:0xf
	s_waitcnt vmcnt(8)
; __device__ __forceinline__ unsigned cvt_pk_bf16(float lo, float hi) { unsigned r; asm volatile("v_cvt_pk_bf16_f32 %0, %1, %2" : "=v"(r) : "v"(lo), "v"(hi)); return r; }
; __device__ __forceinline__ float bf_lo(unsigned w) { return __uint_as_float(w << 16); }
; __device__ __forceinline__ float bf_hi(unsigned w) { return __uint_as_float(w & 0xffff0000u); }
; __global__ void __launch_bounds__(512, 2) trunk_fwd(Args args) {
;     ...
;                 for (int rr = 0; rr < 16; ++rr) {
;                     const int r = r0 + rr;
;                     const u32x4 gb = gb_n, gu = gu_n; const f32x4 pv4 = pv_n;
;                     if (rr < 15) { gb_n = *(const u32x4*)(Z + (size_t)(r + 1) * INP + 768 + c0); gu_n = *(const u32x4*)(Z + (size_t)(r + 1) * INP + 1280 + c0);
;                                    pv_n = *(const f32x4*)(pl + (size_t)(r + 1) * PLE + lane * 4); }
;                     float cv[8], uu[8]; float ss = 0.f;
; #pragma unroll
;                     for (int i = 0; i < 4; ++i) {
;                         uu[2 * i] = bf_lo(gu[i]); uu[2 * i + 1] = bf_hi(gu[i]);
;                         cv[2 * i] = bf_lo(gb[i]) * (w0[2 * i] * uu[2 * i] + w1[2 * i] * u1[2 * i] + w2[2 * i] * u2[2 * i]);
;                         cv[2 * i + 1] = bf_hi(gb[i]) * (w0[2 * i + 1] * uu[2 * i + 1] + w1[2 * i + 1] * u1[2 * i + 1] + w2[2 * i + 1] * u2[2 * i + 1]);
;                     }
; #pragma unroll
;                     for (int i = 0; i < 8; ++i) { ss += cv[i] * cv[i]; u2[i] = u1[i]; u1[i] = uu[i]; }
;                     ss = wave_sum(ss);
;                     const float rc = rsqrtf(ss * (1.0f / 512.0f) + EPS);
;                     u32x4 oc;
; #pragma unroll
;                     for (int i = 0; i < 4; ++i) oc[i] = cvt_pk_bf16(cv[2 * i] * rc, cv[2 * i + 1] * rc);
;                     *(u32x4*)(MIX + (size_t)r * 1024 + 512 + c0) = oc;
;                     u32x2 pw; pw.x = cvt_pk_bf16(pv4[0], pv4[1]); pw.y = cvt_pk_bf16(pv4[2], pv4[3]);
;                     *(u32x2*)(PB + (size_t)r * PLE + lane * 4) = pw;
;                 }
	v_lshlrev_b32_e32 v188, 16, v30
	v_and_b32_e32 v189, 0xffff0000, v30
	v_add_f32_dpp v148, v148, v148 quad_perm:[2,3,0,1] row_mask:0xf bank_mask:0xf
	v_lshlrev_b32_e32 v190, 16, v31
	v_and_b32_e32 v191, 0xffff0000, v31
	v_lshlrev_b32_e32 v192, 16, v32
	v_add_f32_dpp v148, v148, v148 row_half_mirror row_mask:0xf bank_mask:0xf
	v_and_b32_e32 v193, 0xffff0000, v32
	v_lshlrev_b32_e32 v194, 16, v33
	v_add_f32_dpp v148, v148, v148 row_mirror row_mask:0xf bank_mask:0xf
	v_and_b32_e32 v195, 0xffff0000, v33
	v_mul_f32_e32 v34, v164, v188
	v_add_f32_dpp v148, v148, v148 row_bcast:15 row_mask:0xa bank_mask:0xf
	v_mul_f32_e32 v35, v165, v189
	v_mul_f32_e32 v36, v166, v190
	v_add_f32_dpp v148, v148, v148 row_bcast:31 row_mask:0xc bank_mask:0xf
	v_mul_f32_e32 v37, v167, v191
	v_mul_f32_e32 v38, v168, v192
	v_readlane_b32 s0, v148, 63
	v_mul_f32_e32 v39, v169, v193
	v_mul_f32_e32 v40, v170, v194
	v_mov_b32_e32 v148, s0
	v_mul_f32_e32 v41, v171, v195
	v_fmac_f32_e32 v34, v172, v204
	v_fmamk_f32 v148, v148, 0x3b000000, v162
	v_fmac_f32_e32 v35, v173, v205
	v_fmac_f32_e32 v36, v174, v206
	v_mul_f32_e32 v43, 0x4b800000, v148
	v_fmac_f32_e32 v37, v175, v207
	v_fmac_f32_e32 v38, v176, v208
	v_cmp_gt_f32_e32 vcc, s31, v148
	v_fmac_f32_e32 v39, v177, v209
	v_fmac_f32_e32 v40, v178, v210
	v_cndmask_b32_e32 v148, v148, v43, vcc
	v_fmac_f32_e32 v41, v179, v211
	v_fmac_f32_e32 v34, v180, v196
	v_rsq_f32_e32 v148, v148
	v_fmac_f32_e32 v35, v181, v197
	v_fmac_f32_e32 v36, v182, v198
	v_mul_f32_e32 v43, 0x45800000, v148
	v_fmac_f32_e32 v37, v183, v199
	v_fmac_f32_e32 v38, v184, v200
	v_cndmask_b32_e32 v149, v148, v43, vcc
	v_fmac_f32_e32 v39, v185, v201
	v_fmac_f32_e32 v40, v186, v202
	v_mul_f32_e32 v140, v149, v140
	v_fmac_f32_e32 v41, v187, v203
	v_lshlrev_b32_e32 v150, 16, v14
	v_mul_f32_e32 v141, v149, v141
	v_and_b32_e32 v151, 0xffff0000, v14
	v_mul_f32_e32 v34, v150, v34
	v_mul_f32_e32 v142, v149, v142
	v_mul_f32_e32 v35, v151, v35
	v_lshlrev_b32_e32 v150, 16, v15
	v_mul_f32_e32 v143, v149, v143
	v_and_b32_e32 v151, 0xffff0000, v15
	v_mul_f32_e32 v36, v150, v36
	v_mul_f32_e32 v144, v149, v144
	v_mul_f32_e32 v37, v151, v37
	v_lshlrev_b32_e32 v150, 16, v16
	v_mul_f32_e32 v145, v149, v145
	v_and_b32_e32 v151, 0xffff0000, v16
	v_mul_f32_e32 v38, v150, v38
	v_mul_f32_e32 v146, v149, v146
	v_mul_f32_e32 v39, v151, v39
	v_lshlrev_b32_e32 v150, 16, v17
	v_mul_f32_e32 v147, v149, v147
	v_and_b32_e32 v151, 0xffff0000, v17
	v_mul_f32_e32 v40, v150, v40
	v_cvt_pk_bf16_f32 v140, v140, v141
	v_mul_f32_e32 v41, v151, v41
	v_mul_f32_e32 v42, v34, v34
	v_cvt_pk_bf16_f32 v141, v142, v143
	v_fmac_f32_e32 v42, v35, v35
	v_fmac_f32_e32 v42, v36, v36
	v_cvt_pk_bf16_f32 v142, v144, v145
	v_fmac_f32_e32 v42, v37, v37
	v_fmac_f32_e32 v42, v38, v38
	v_cvt_pk_bf16_f32 v143, v146, v147
	v_fmac_f32_e32 v42, v39, v39
	v_fmac_f32_e32 v42, v40, v40
	global_store_dwordx4 v[156:157], v[140:143], off
	v_fmac_f32_e32 v42, v41, v41
	v_mad_i64_i32 v[152:153], s[42:43], s41, v221, v[58:59]
	s_add_u32 s41, s41, 1
	global_load_dwordx4 v[14:17], v[152:153], off offset:1536
	global_load_dwordx4 v[30:33], v[152:153], off offset:2560
	s_nop 1
	v_add_f32_dpp v42, v42, v42 quad_perm:[1,0,3,2] row_mask:0xf bank_mask:0xf
	s_waitcnt vmcnt(9)
	v_lshlrev_b32_e32 v196, 16, v18
	v_and_b32_e32 v197, 0xffff0000, v18
	v_add_f32_dpp v42, v42, v42 quad_perm:[2,3,0,1] row_mask:0xf bank_mask:0xf
	v_lshlrev_b32_e32 v198, 16, v19
	v_and_b32_e32 v199, 0xffff0000, v19
	v_add_f32_dpp v42, v42, v42 row_half_mirror row_mask:0xf bank_mask:0xf
	v_lshlrev_b32_e32 v200, 16, v20
	v_and_b32_e32 v201, 0xffff0000, v20
	v_add_f32_dpp v42, v42, v42 row_mirror row_mask:0xf bank_mask:0xf
	v_lshlrev_b32_e32 v202, 16, v21
	v_and_b32_e32 v203, 0xffff0000, v21
	v_add_f32_dpp v42, v42, v42 row_bcast:15 row_mask:0xa bank_mask:0xf
	v_mul_f32_e32 v140, v164, v196
	v_mul_f32_e32 v141, v165, v197
	v_add_f32_dpp v42, v42, v42 row_bcast:31 row_mask:0xc bank_mask:0xf
	v_mul_f32_e32 v142, v166, v198
	v_mul_f32_e32 v143, v167, v199
	v_readlane_b32 s0, v42, 63
	v_mul_f32_e32 v144, v168, v200
	v_mul_f32_e32 v145, v169, v201
	v_mov_b32_e32 v42, s0
	v_mul_f32_e32 v146, v170, v202
	v_mul_f32_e32 v147, v171, v203
	v_fmamk_f32 v42, v42, 0x3b000000, v162
	v_fmac_f32_e32 v140, v172, v188
	v_fmac_f32_e32 v141, v173, v189
	v_mul_f32_e32 v43, 0x4b800000, v42
	v_fmac_f32_e32 v142, v174, v190
	v_fmac_f32_e32 v143, v175, v191
	v_cmp_gt_f32_e32 vcc, s31, v42
	v_fmac_f32_e32 v144, v176, v192
	v_fmac_f32_e32 v145, v177, v193
	v_cndmask_b32_e32 v42, v42, v43, vcc
	v_fmac_f32_e32 v146, v178, v194
	v_fmac_f32_e32 v147, v179, v195
	v_rsq_f32_e32 v42, v42
	v_fmac_f32_e32 v140, v180, v204
	v_fmac_f32_e32 v141, v181, v205
	v_mul_f32_e32 v43, 0x45800000, v42
	v_fmac_f32_e32 v142, v182, v206
	v_fmac_f32_e32 v143, v183, v207
	v_cndmask_b32_e32 v149, v42, v43, vcc
	v_fmac_f32_e32 v144, v184, v208
	v_fmac_f32_e32 v145, v185, v209
	v_mul_f32_e32 v34, v149, v34
	v_fmac_f32_e32 v146, v186, v210
	v_fmac_f32_e32 v147, v187, v211
	v_mul_f32_e32 v35, v149, v35
	v_lshlrev_b32_e32 v150, 16, v2
	v_and_b32_e32 v151, 0xffff0000, v2
	v_mul_f32_e32 v36, v149, v36
	v_mul_f32_e32 v140, v150, v140
	v_mul_f32_e32 v141, v151, v141
	v_mul_f32_e32 v37, v149, v37
	v_lshlrev_b32_e32 v150, 16, v3
	v_and_b32_e32 v151, 0xffff0000, v3
	v_mul_f32_e32 v38, v149, v38
	v_mul_f32_e32 v142, v150, v142
	v_mul_f32_e32 v143, v151, v143
	v_mul_f32_e32 v39, v149, v39
	v_lshlrev_b32_e32 v150, 16, v4
	v_and_b32_e32 v151, 0xffff0000, v4
	v_mul_f32_e32 v40, v149, v40
	v_mul_f32_e32 v144, v150, v144
	v_mul_f32_e32 v145, v151, v145
	v_mul_f32_e32 v41, v149, v41
	v_lshlrev_b32_e32 v150, 16, v5
	v_and_b32_e32 v151, 0xffff0000, v5
	v_cvt_pk_bf16_f32 v34, v34, v35
	v_mul_f32_e32 v146, v150, v146
	v_mul_f32_e32 v147, v151, v147
	v_cvt_pk_bf16_f32 v35, v36, v37
	v_mul_f32_e32 v148, v140, v140
	v_fmac_f32_e32 v148, v141, v141
	v_cvt_pk_bf16_f32 v36, v38, v39
	v_fmac_f32_e32 v148, v142, v142
	v_fmac_f32_e32 v148, v143, v143
	v_cvt_pk_bf16_f32 v37, v40, v41
	v_fmac_f32_e32 v148, v144, v144
	v_fmac_f32_e32 v148, v145, v145
	global_store_dwordx4 v[156:157], v[34:37], off offset:2048
	v_fmac_f32_e32 v148, v146, v146
	v_fmac_f32_e32 v148, v147, v147
	v_lshl_add_u64 v[156:157], v[156:157], 0, s[20:21]
	v_mad_i64_i32 v[152:153], s[42:43], s41, v221, v[58:59]
	s_add_u32 s41, s41, 1
	global_load_dwordx4 v[2:5], v[152:153], off offset:1536
	global_load_dwordx4 v[18:21], v[152:153], off offset:2560
	s_nop 1
	v_add_f32_dpp v148, v148, v148 quad_perm:[1,0,3,2] row_mask:0xf bank_mask:0xf
	s_waitcnt vmcnt(9)
; __device__ __forceinline__ unsigned cvt_pk_bf16(float lo, float hi) { unsigned r; asm volatile("v_cvt_pk_bf16_f32 %0, %1, %2" : "=v"(r) : "v"(lo), "v"(hi)); return r; }
; __device__ __forceinline__ float bf_lo(unsigned w) { return __uint_as_float(w << 16); }
; __device__ __forceinline__ float bf_hi(unsigned w) { return __uint_as_float(w & 0xffff0000u); }
; __global__ void __launch_bounds__(512, 2) trunk_fwd(Args args) {
;     ...
;                 for (int rr = 0; rr < 16; ++rr) {
;                     const int r = r0 + rr;
;                     const u32x4 gb = gb_n, gu = gu_n; const f32x4 pv4 = pv_n;
;                     if (rr < 15) { gb_n = *(const u32x4*)(Z + (size_t)(r + 1) * INP + 768 + c0); gu_n = *(const u32x4*)(Z + (size_t)(r + 1) * INP + 1280 + c0);
;                                    pv_n = *(const f32x4*)(pl + (size_t)(r + 1) * PLE + lane * 4); }
;                     float cv[8], uu[8]; float ss = 0.f;
; #pragma unroll
;                     for (int i = 0; i < 4; ++i) {
;                         uu[2 * i] = bf_lo(gu[i]); uu[2 * i + 1] = bf_hi(gu[i]);
;                         cv[2 * i] = bf_lo(gb[i]) * (w0[2 * i] * uu[2 * i] + w1[2 * i] * u1[2 * i] + w2[2 * i] * u2[2 * i]);
;                         cv[2 * i + 1] = bf_hi(gb[i]) * (w0[2 * i + 1] * uu[2 * i + 1] + w1[2 * i + 1] * u1[2 * i + 1] + w2[2 * i + 1] * u2[2 * i + 1]);
;                     }
; #pragma unroll
;                     for (int i = 0; i < 8; ++i) { ss += cv[i] * cv[i]; u2[i] = u1[i]; u1[i] = uu[i]; }
;                     ss = wave_sum(ss);
;                     const float rc = rsqrtf(ss * (1.0f / 512.0f) + EPS);
;                     u32x4 oc;
; #pragma unroll
;                     for (int i = 0; i < 4; ++i) oc[i] = cvt_pk_bf16(cv[2 * i] * rc, cv[2 * i + 1] * rc);
;                     *(u32x4*)(MIX + (size_t)r * 1024 + 512 + c0) = oc;
;                     u32x2 pw; pw.x = cvt_pk_bf16(pv4[0], pv4[1]); pw.y = cvt_pk_bf16(pv4[2], pv4[3]);
;                     *(u32x2*)(PB + (size_t)r * PLE + lane * 4) = pw;
;                 }
	v_lshlrev_b32_e32 v204, 16, v22
	v_and_b32_e32 v205, 0xffff0000, v22
	v_add_f32_dpp v148, v148, v148 quad_perm:[2,3,0,1] row_mask:0xf bank_mask:0xf
	v_lshlrev_b32_e32 v206, 16, v23
	v_and_b32_e32 v207, 0xffff0000, v23
	v_lshlrev_b32_e32 v208, 16, v24
	v_add_f32_dpp v148, v148, v148 row_half_mirror row_mask:0xf bank_mask:0xf
	v_and_b32_e32 v209, 0xffff0000, v24
	v_lshlrev_b32_e32 v210, 16, v25
	v_add_f32_dpp v148, v148, v148 row_mirror row_mask:0xf bank_mask:0xf
	v_and_b32_e32 v211, 0xffff0000, v25
	v_mul_f32_e32 v34, v164, v204
	v_add_f32_dpp v148, v148, v148 row_bcast:15 row_mask:0xa bank_mask:0xf
	v_mul_f32_e32 v35, v165, v205
	v_mul_f32_e32 v36, v166, v206
	v_add_f32_dpp v148, v148, v148 row_bcast:31 row_mask:0xc bank_mask:0xf
	v_mul_f32_e32 v37, v167, v207
	v_mul_f32_e32 v38, v168, v208
	v_readlane_b32 s0, v148, 63
	v_mul_f32_e32 v39, v169, v209
	v_mul_f32_e32 v40, v170, v210
	v_mov_b32_e32 v148, s0
	v_mul_f32_e32 v41, v171, v211
	v_fmac_f32_e32 v34, v172, v196
	v_fmamk_f32 v148, v148, 0x3b000000, v162
	v_fmac_f32_e32 v35, v173, v197
	v_fmac_f32_e32 v36, v174, v198
	v_mul_f32_e32 v43, 0x4b800000, v148
	v_fmac_f32_e32 v37, v175, v199
	v_fmac_f32_e32 v38, v176, v200
	v_cmp_gt_f32_e32 vcc, s31, v148
	v_fmac_f32_e32 v39, v177, v201
	v_fmac_f32_e32 v40, v178, v202
	v_cndmask_b32_e32 v148, v148, v43, vcc
	v_fmac_f32_e32 v41, v179, v203
	v_fmac_f32_e32 v34, v180, v188
	v_rsq_f32_e32 v148, v148
	v_fmac_f32_e32 v35, v181, v189
	v_fmac_f32_e32 v36, v182, v190
	v_mul_f32_e32 v43, 0x45800000, v148
	v_fmac_f32_e32 v37, v183, v191
	v_fmac_f32_e32 v38, v184, v192
	v_cndmask_b32_e32 v149, v148, v43, vcc
	v_fmac_f32_e32 v39, v185, v193
	v_fmac_f32_e32 v40, v186, v194
	v_mul_f32_e32 v140, v149, v140
	v_fmac_f32_e32 v41, v187, v195
	v_lshlrev_b32_e32 v150, 16, v6
	v_mul_f32_e32 v141, v149, v141
	v_and_b32_e32 v151, 0xffff0000, v6
	v_mul_f32_e32 v34, v150, v34
	v_mul_f32_e32 v142, v149, v142
	v_mul_f32_e32 v35, v151, v35
	v_lshlrev_b32_e32 v150, 16, v7
	v_mul_f32_e32 v143, v149, v143
	v_and_b32_e32 v151, 0xffff0000, v7
	v_mul_f32_e32 v36, v150, v36
	v_mul_f32_e32 v144, v149, v144
	v_mul_f32_e32 v37, v151, v37
	v_lshlrev_b32_e32 v150, 16, v8
	v_mul_f32_e32 v145, v149, v145
	v_and_b32_e32 v151, 0xffff0000, v8
	v_mul_f32_e32 v38, v150, v38
	v_mul_f32_e32 v146, v149, v146
	v_mul_f32_e32 v39, v151, v39
	v_lshlrev_b32_e32 v150, 16, v9
	v_mul_f32_e32 v147, v149, v147
	v_and_b32_e32 v151, 0xffff0000, v9
	v_mul_f32_e32 v40, v150, v40
	v_cvt_pk_bf16_f32 v140, v140, v141
	v_mul_f32_e32 v41, v151, v41
	v_mul_f32_e32 v42, v34, v34
	v_cvt_pk_bf16_f32 v141, v142, v143
	v_fmac_f32_e32 v42, v35, v35
	v_fmac_f32_e32 v42, v36, v36
	v_cvt_pk_bf16_f32 v142, v144, v145
	v_fmac_f32_e32 v42, v37, v37
	v_fmac_f32_e32 v42, v38, v38
	v_cvt_pk_bf16_f32 v143, v146, v147
	v_fmac_f32_e32 v42, v39, v39
	v_fmac_f32_e32 v42, v40, v40
	global_store_dwordx4 v[156:157], v[140:143], off
	v_fmac_f32_e32 v42, v41, v41
	v_mad_i64_i32 v[152:153], s[42:43], s41, v221, v[58:59]
	s_add_u32 s41, s41, 1
	global_load_dwordx4 v[6:9], v[152:153], off offset:1536
	global_load_dwordx4 v[22:25], v[152:153], off offset:2560
	s_nop 1
	v_add_f32_dpp v42, v42, v42 quad_perm:[1,0,3,2] row_mask:0xf bank_mask:0xf
	s_waitcnt vmcnt(9)
	v_lshlrev_b32_e32 v188, 16, v26
	v_and_b32_e32 v189, 0xffff0000, v26
	v_add_f32_dpp v42, v42, v42 quad_perm:[2,3,0,1] row_mask:0xf bank_mask:0xf
	v_lshlrev_b32_e32 v190, 16, v27
	v_and_b32_e32 v191, 0xffff0000, v27
	v_add_f32_dpp v42, v42, v42 row_half_mirror row_mask:0xf bank_mask:0xf
	v_lshlrev_b32_e32 v192, 16, v28
	v_and_b32_e32 v193, 0xffff0000, v28
	v_add_f32_dpp v42, v42, v42 row_mirror row_mask:0xf bank_mask:0xf
	v_lshlrev_b32_e32 v194, 16, v29
	v_and_b32_e32 v195, 0xffff0000, v29
	v_add_f32_dpp v42, v42, v42 row_bcast:15 row_mask:0xa bank_mask:0xf
	v_mul_f32_e32 v140, v164, v188
	v_mul_f32_e32 v141, v165, v189
	v_add_f32_dpp v42, v42, v42 row_bcast:31 row_mask:0xc bank_mask:0xf
	v_mul_f32_e32 v142, v166, v190
	v_mul_f32_e32 v143, v167, v191
	v_readlane_b32 s0, v42, 63
	v_mul_f32_e32 v144, v168, v192
	v_mul_f32_e32 v145, v169, v193
	v_mov_b32_e32 v42, s0
	v_mul_f32_e32 v146, v170, v194
	v_mul_f32_e32 v147, v171, v195
	v_fmamk_f32 v42, v42, 0x3b000000, v162
	v_fmac_f32_e32 v140, v172, v204
	v_fmac_f32_e32 v141, v173, v205
	v_mul_f32_e32 v43, 0x4b800000, v42
	v_fmac_f32_e32 v142, v174, v206
	v_fmac_f32_e32 v143, v175, v207
	v_cmp_gt_f32_e32 vcc, s31, v42
	v_fmac_f32_e32 v144, v176, v208
	v_fmac_f32_e32 v145, v177, v209
	v_cndmask_b32_e32 v42, v42, v43, vcc
	v_fmac_f32_e32 v146, v178, v210
	v_fmac_f32_e32 v147, v179, v211
	v_rsq_f32_e32 v42, v42
	v_fmac_f32_e32 v140, v180, v196
	v_fmac_f32_e32 v141, v181, v197
	v_mul_f32_e32 v43, 0x45800000, v42
	v_fmac_f32_e32 v142, v182, v198
	v_fmac_f32_e32 v143, v183, v199
	v_cndmask_b32_e32 v149, v42, v43, vcc
	v_fmac_f32_e32 v144, v184, v200
	v_fmac_f32_e32 v145, v185, v201
	v_mul_f32_e32 v34, v149, v34
	v_fmac_f32_e32 v146, v186, v202
	v_fmac_f32_e32 v147, v187, v203
	v_mul_f32_e32 v35, v149, v35
	v_lshlrev_b32_e32 v150, 16, v10
	v_and_b32_e32 v151, 0xffff0000, v10
	v_mul_f32_e32 v36, v149, v36
	v_mul_f32_e32 v140, v150, v140
	v_mul_f32_e32 v141, v151, v141
	v_mul_f32_e32 v37, v149, v37
	v_lshlrev_b32_e32 v150, 16, v11
	v_and_b32_e32 v151, 0xffff0000, v11
	v_mul_f32_e32 v38, v149, v38
	v_mul_f32_e32 v142, v150, v142
	v_mul_f32_e32 v143, v151, v143
	v_mul_f32_e32 v39, v149, v39
	v_lshlrev_b32_e32 v150, 16, v12
	v_and_b32_e32 v151, 0xffff0000, v12
	v_mul_f32_e32 v40, v149, v40
	v_mul_f32_e32 v144, v150, v144
	v_mul_f32_e32 v145, v151, v145
	v_mul_f32_e32 v41, v149, v41
	v_lshlrev_b32_e32 v150, 16, v13
	v_and_b32_e32 v151, 0xffff0000, v13
	v_cvt_pk_bf16_f32 v34, v34, v35
	v_mul_f32_e32 v146, v150, v146
	v_mul_f32_e32 v147, v151, v147
	v_cvt_pk_bf16_f32 v35, v36, v37
	v_mul_f32_e32 v148, v140, v140
	v_fmac_f32_e32 v148, v141, v141
	v_cvt_pk_bf16_f32 v36, v38, v39
	v_fmac_f32_e32 v148, v142, v142
	v_fmac_f32_e32 v148, v143, v143
	v_cvt_pk_bf16_f32 v37, v40, v41
	v_fmac_f32_e32 v148, v144, v144
	v_fmac_f32_e32 v148, v145, v145
	global_store_dwordx4 v[156:157], v[34:37], off offset:2048
	v_fmac_f32_e32 v148, v146, v146
	v_fmac_f32_e32 v148, v147, v147
	v_lshl_add_u64 v[156:157], v[156:157], 0, s[20:21]
	v_mad_i64_i32 v[152:153], s[42:43], s41, v221, v[58:59]
	s_add_u32 s41, s41, 1
	global_load_dwordx4 v[10:13], v[152:153], off offset:1536
	global_load_dwordx4 v[26:29], v[152:153], off offset:2560
	s_nop 1
	v_add_f32_dpp v148, v148, v148 quad_perm:[1,0,3,2] row_mask:0xf bank_mask:0xf
	s_waitcnt vmcnt(9)
; __device__ __forceinline__ unsigned cvt_pk_bf16(float lo, float hi) { unsigned r; asm volatile("v_cvt_pk_bf16_f32 %0, %1, %2" : "=v"(r) : "v"(lo), "v"(hi)); return r; }
; __device__ __forceinline__ float bf_lo(unsigned w) { return __uint_as_float(w << 16); }
; __device__ __forceinline__ float bf_hi(unsigned w) { return __uint_as_float(w & 0xffff0000u); }
; __global__ void __launch_bounds__(512, 2) trunk_fwd(Args args) {
;     ...
;                 for (int rr = 0; rr < 16; ++rr) {
;                     const int r = r0 + rr;
;                     const u32x4 gb = gb_n, gu = gu_n; const f32x4 pv4 = pv_n;
;                     if (rr < 15) { gb_n = *(const u32x4*)(Z + (size_t)(r + 1) * INP + 768 + c0); gu_n = *(const u32x4*)(Z + (size_t)(r + 1) * INP + 1280 + c0);
;                                    pv_n = *(const f32x4*)(pl + (size_t)(r + 1) * PLE + lane * 4); }
;                     float cv[8], uu[8]; float ss = 0.f;
; #pragma unroll
;                     for (int i = 0; i < 4; ++i) {
;                         uu[2 * i] = bf_lo(gu[i]); uu[2 * i + 1] = bf_hi(gu[i]);
;                         cv[2 * i] = bf_lo(gb[i]) * (w0[2 * i] * uu[2 * i] + w1[2 * i] * u1[2 * i] + w2[2 * i] * u2[2 * i]);
;                         cv[2 * i + 1] = bf_hi(gb[i]) * (w0[2 * i + 1] * uu[2 * i + 1] + w1[2 * i + 1] * u1[2 * i + 1] + w2[2 * i + 1] * u2[2 * i + 1]);
;                     }
; #pragma unroll
;                     for (int i = 0; i < 8; ++i) { ss += cv[i] * cv[i]; u2[i] = u1[i]; u1[i] = uu[i]; }
;                     ss = wave_sum(ss);
;                     const float rc = rsqrtf(ss * (1.0f / 512.0f) + EPS);
;                     u32x4 oc;
; #pragma unroll
;                     for (int i = 0; i < 4; ++i) oc[i] = cvt_pk_bf16(cv[2 * i] * rc, cv[2 * i + 1] * rc);
;                     *(u32x4*)(MIX + (size_t)r * 1024 + 512 + c0) = oc;
;                     u32x2 pw; pw.x = cvt_pk_bf16(pv4[0], pv4[1]); pw.y = cvt_pk_bf16(pv4[2], pv4[3]);
;                     *(u32x2*)(PB + (size_t)r * PLE + lane * 4) = pw;
;                 }
	v_lshlrev_b32_e32 v196, 16, v30
	v_and_b32_e32 v197, 0xffff0000, v30
	v_add_f32_dpp v148, v148, v148 quad_perm:[2,3,0,1] row_mask:0xf bank_mask:0xf
	v_lshlrev_b32_e32 v198, 16, v31
	v_and_b32_e32 v199, 0xffff0000, v31
	v_lshlrev_b32_e32 v200, 16, v32
	v_add_f32_dpp v148, v148, v148 row_half_mirror row_mask:0xf bank_mask:0xf
	v_and_b32_e32 v201, 0xffff0000, v32
	v_lshlrev_b32_e32 v202, 16, v33
	v_add_f32_dpp v148, v148, v148 row_mirror row_mask:0xf bank_mask:0xf
	v_and_b32_e32 v203, 0xffff0000, v33
	v_mul_f32_e32 v34, v164, v196
	v_add_f32_dpp v148, v148, v148 row_bcast:15 row_mask:0xa bank_mask:0xf
	v_mul_f32_e32 v35, v165, v197
	v_mul_f32_e32 v36, v166, v198
	v_add_f32_dpp v148, v148, v148 row_bcast:31 row_mask:0xc bank_mask:0xf
	v_mul_f32_e32 v37, v167, v199
	v_mul_f32_e32 v38, v168, v200
	v_readlane_b32 s0, v148, 63
	v_mul_f32_e32 v39, v169, v201
	v_mul_f32_e32 v40, v170, v202
	v_mov_b32_e32 v148, s0
	v_mul_f32_e32 v41, v171, v203
	v_fmac_f32_e32 v34, v172, v188
	v_fmamk_f32 v148, v148, 0x3b000000, v162
	v_fmac_f32_e32 v35, v173, v189
	v_fmac_f32_e32 v36, v174, v190
	v_mul_f32_e32 v43, 0x4b800000, v148
	v_fmac_f32_e32 v37, v175, v191
	v_fmac_f32_e32 v38, v176, v192
	v_cmp_gt_f32_e32 vcc, s31, v148
	v_fmac_f32_e32 v39, v177, v193
	v_fmac_f32_e32 v40, v178, v194
	v_cndmask_b32_e32 v148, v148, v43, vcc
	v_fmac_f32_e32 v41, v179, v195
	v_fmac_f32_e32 v34, v180, v204
	v_rsq_f32_e32 v148, v148
	v_fmac_f32_e32 v35, v181, v205
	v_fmac_f32_e32 v36, v182, v206
	v_mul_f32_e32 v43, 0x45800000, v148
	v_fmac_f32_e32 v37, v183, v207
	v_fmac_f32_e32 v38, v184, v208
	v_cndmask_b32_e32 v149, v148, v43, vcc
	v_fmac_f32_e32 v39, v185, v209
	v_fmac_f32_e32 v40, v186, v210
	v_mul_f32_e32 v140, v149, v140
	v_fmac_f32_e32 v41, v187, v211
	v_lshlrev_b32_e32 v150, 16, v14
	v_mul_f32_e32 v141, v149, v141
	v_and_b32_e32 v151, 0xffff0000, v14
	v_mul_f32_e32 v34, v150, v34
	v_mul_f32_e32 v142, v149, v142
	v_mul_f32_e32 v35, v151, v35
	v_lshlrev_b32_e32 v150, 16, v15
	v_mul_f32_e32 v143, v149, v143
	v_and_b32_e32 v151, 0xffff0000, v15
	v_mul_f32_e32 v36, v150, v36
	v_mul_f32_e32 v144, v149, v144
	v_mul_f32_e32 v37, v151, v37
	v_lshlrev_b32_e32 v150, 16, v16
	v_mul_f32_e32 v145, v149, v145
	v_and_b32_e32 v151, 0xffff0000, v16
	v_mul_f32_e32 v38, v150, v38
	v_mul_f32_e32 v146, v149, v146
	v_mul_f32_e32 v39, v151, v39
	v_lshlrev_b32_e32 v150, 16, v17
	v_mul_f32_e32 v147, v149, v147
	v_and_b32_e32 v151, 0xffff0000, v17
	v_mul_f32_e32 v40, v150, v40
	v_cvt_pk_bf16_f32 v140, v140, v141
	v_mul_f32_e32 v41, v151, v41
	v_mul_f32_e32 v42, v34, v34
	v_cvt_pk_bf16_f32 v141, v142, v143
	v_fmac_f32_e32 v42, v35, v35
	v_fmac_f32_e32 v42, v36, v36
	v_cvt_pk_bf16_f32 v142, v144, v145
	v_fmac_f32_e32 v42, v37, v37
	v_fmac_f32_e32 v42, v38, v38
	v_cvt_pk_bf16_f32 v143, v146, v147
	v_fmac_f32_e32 v42, v39, v39
	v_fmac_f32_e32 v42, v40, v40
	global_store_dwordx4 v[156:157], v[140:143], off
	v_fmac_f32_e32 v42, v41, v41
	v_mad_i64_i32 v[152:153], s[42:43], s41, v221, v[58:59]
	s_add_u32 s41, s41, 1
	global_load_dwordx4 v[14:17], v[152:153], off offset:1536
	global_load_dwordx4 v[30:33], v[152:153], off offset:2560
	s_nop 1
	v_add_f32_dpp v42, v42, v42 quad_perm:[1,0,3,2] row_mask:0xf bank_mask:0xf
	s_waitcnt vmcnt(9)
	v_lshlrev_b32_e32 v204, 16, v18
	v_and_b32_e32 v205, 0xffff0000, v18
	v_add_f32_dpp v42, v42, v42 quad_perm:[2,3,0,1] row_mask:0xf bank_mask:0xf
	v_lshlrev_b32_e32 v206, 16, v19
	v_and_b32_e32 v207, 0xffff0000, v19
	v_add_f32_dpp v42, v42, v42 row_half_mirror row_mask:0xf bank_mask:0xf
	v_lshlrev_b32_e32 v208, 16, v20
	v_and_b32_e32 v209, 0xffff0000, v20
	v_add_f32_dpp v42, v42, v42 row_mirror row_mask:0xf bank_mask:0xf
	v_lshlrev_b32_e32 v210, 16, v21
	v_and_b32_e32 v211, 0xffff0000, v21
	v_add_f32_dpp v42, v42, v42 row_bcast:15 row_mask:0xa bank_mask:0xf
	v_mul_f32_e32 v140, v164, v204
	v_mul_f32_e32 v141, v165, v205
	v_add_f32_dpp v42, v42, v42 row_bcast:31 row_mask:0xc bank_mask:0xf
	v_mul_f32_e32 v142, v166, v206
	v_mul_f32_e32 v143, v167, v207
	v_readlane_b32 s0, v42, 63
	v_mul_f32_e32 v144, v168, v208
	v_mul_f32_e32 v145, v169, v209
	v_mov_b32_e32 v42, s0
	v_mul_f32_e32 v146, v170, v210
	v_mul_f32_e32 v147, v171, v211
	v_fmamk_f32 v42, v42, 0x3b000000, v162
	v_fmac_f32_e32 v140, v172, v196
	v_fmac_f32_e32 v141, v173, v197
	v_mul_f32_e32 v43, 0x4b800000, v42
	v_fmac_f32_e32 v142, v174, v198
	v_fmac_f32_e32 v143, v175, v199
	v_cmp_gt_f32_e32 vcc, s31, v42
	v_fmac_f32_e32 v144, v176, v200
	v_fmac_f32_e32 v145, v177, v201
	v_cndmask_b32_e32 v42, v42, v43, vcc
	v_fmac_f32_e32 v146, v178, v202
	v_fmac_f32_e32 v147, v179, v203
	v_rsq_f32_e32 v42, v42
	v_fmac_f32_e32 v140, v180, v188
	v_fmac_f32_e32 v141, v181, v189
	v_mul_f32_e32 v43, 0x45800000, v42
	v_fmac_f32_e32 v142, v182, v190
	v_fmac_f32_e32 v143, v183, v191
	v_cndmask_b32_e32 v149, v42, v43, vcc
	v_fmac_f32_e32 v144, v184, v192
	v_fmac_f32_e32 v145, v185, v193
	v_mul_f32_e32 v34, v149, v34
	v_fmac_f32_e32 v146, v186, v194
	v_fmac_f32_e32 v147, v187, v195
	v_mul_f32_e32 v35, v149, v35
	v_lshlrev_b32_e32 v150, 16, v2
	v_and_b32_e32 v151, 0xffff0000, v2
	v_mul_f32_e32 v36, v149, v36
	v_mul_f32_e32 v140, v150, v140
	v_mul_f32_e32 v141, v151, v141
	v_mul_f32_e32 v37, v149, v37
	v_lshlrev_b32_e32 v150, 16, v3
	v_and_b32_e32 v151, 0xffff0000, v3
	v_mul_f32_e32 v38, v149, v38
	v_mul_f32_e32 v142, v150, v142
	v_mul_f32_e32 v143, v151, v143
	v_mul_f32_e32 v39, v149, v39
	v_lshlrev_b32_e32 v150, 16, v4
	v_and_b32_e32 v151, 0xffff0000, v4
	v_mul_f32_e32 v40, v149, v40
	v_mul_f32_e32 v144, v150, v144
	v_mul_f32_e32 v145, v151, v145
	v_mul_f32_e32 v41, v149, v41
	v_lshlrev_b32_e32 v150, 16, v5
	v_and_b32_e32 v151, 0xffff0000, v5
	v_cvt_pk_bf16_f32 v34, v34, v35
	v_mul_f32_e32 v146, v150, v146
	v_mul_f32_e32 v147, v151, v147
	v_cvt_pk_bf16_f32 v35, v36, v37
	v_mul_f32_e32 v148, v140, v140
	v_fmac_f32_e32 v148, v141, v141
	v_cvt_pk_bf16_f32 v36, v38, v39
	v_fmac_f32_e32 v148, v142, v142
	v_fmac_f32_e32 v148, v143, v143
	v_cvt_pk_bf16_f32 v37, v40, v41
	v_fmac_f32_e32 v148, v144, v144
	v_fmac_f32_e32 v148, v145, v145
	global_store_dwordx4 v[156:157], v[34:37], off offset:2048
	v_fmac_f32_e32 v148, v146, v146
	v_fmac_f32_e32 v148, v147, v147
	v_lshl_add_u64 v[156:157], v[156:157], 0, s[20:21]
	v_mad_i64_i32 v[152:153], s[42:43], s41, v221, v[58:59]
	s_add_u32 s41, s41, 1
	global_load_dwordx4 v[2:5], v[152:153], off offset:1536
	global_load_dwordx4 v[18:21], v[152:153], off offset:2560
	s_nop 1
	v_add_f32_dpp v148, v148, v148 quad_perm:[1,0,3,2] row_mask:0xf bank_mask:0xf
	s_waitcnt vmcnt(9)
; __device__ __forceinline__ unsigned cvt_pk_bf16(float lo, float hi) { unsigned r; asm volatile("v_cvt_pk_bf16_f32 %0, %1, %2" : "=v"(r) : "v"(lo), "v"(hi)); return r; }
; __device__ __forceinline__ float bf_lo(unsigned w) { return __uint_as_float(w << 16); }
; __device__ __forceinline__ float bf_hi(unsigned w) { return __uint_as_float(w & 0xffff0000u); }
; __global__ void __launch_bounds__(512, 2) trunk_fwd(Args args) {
;     ...
;                 for (int rr = 0; rr < 16; ++rr) {
;                     const int r = r0 + rr;
;                     const u32x4 gb = gb_n, gu = gu_n; const f32x4 pv4 = pv_n;
;                     if (rr < 15) { gb_n = *(const u32x4*)(Z + (size_t)(r + 1) * INP + 768 + c0); gu_n = *(const u32x4*)(Z + (size_t)(r + 1) * INP + 1280 + c0);
;                                    pv_n = *(const f32x4*)(pl + (size_t)(r + 1) * PLE + lane * 4); }
;                     float cv[8], uu[8]; float ss = 0.f;
; #pragma unroll
;                     for (int i = 0; i < 4; ++i) {
;                         uu[2 * i] = bf_lo(gu[i]); uu[2 * i + 1] = bf_hi(gu[i]);
;                         cv[2 * i] = bf_lo(gb[i]) * (w0[2 * i] * uu[2 * i] + w1[2 * i] * u1[2 * i] + w2[2 * i] * u2[2 * i]);
;                         cv[2 * i + 1] = bf_hi(gb[i]) * (w0[2 * i + 1] * uu[2 * i + 1] + w1[2 * i + 1] * u1[2 * i + 1] + w2[2 * i + 1] * u2[2 * i + 1]);
;                     }
; #pragma unroll
;                     for (int i = 0; i < 8; ++i) { ss += cv[i] * cv[i]; u2[i] = u1[i]; u1[i] = uu[i]; }
;                     ss = wave_sum(ss);
;                     const float rc = rsqrtf(ss * (1.0f / 512.0f) + EPS);
;                     u32x4 oc;
; #pragma unroll
;                     for (int i = 0; i < 4; ++i) oc[i] = cvt_pk_bf16(cv[2 * i] * rc, cv[2 * i + 1] * rc);
;                     *(u32x4*)(MIX + (size_t)r * 1024 + 512 + c0) = oc;
;                     u32x2 pw; pw.x = cvt_pk_bf16(pv4[0], pv4[1]); pw.y = cvt_pk_bf16(pv4[2], pv4[3]);
;                     *(u32x2*)(PB + (size_t)r * PLE + lane * 4) = pw;
;                 }
	v_lshlrev_b32_e32 v188, 16, v22
	v_and_b32_e32 v189, 0xffff0000, v22
	v_add_f32_dpp v148, v148, v148 quad_perm:[2,3,0,1] row_mask:0xf bank_mask:0xf
	v_lshlrev_b32_e32 v190, 16, v23
	v_and_b32_e32 v191, 0xffff0000, v23
	v_lshlrev_b32_e32 v192, 16, v24
	v_add_f32_dpp v148, v148, v148 row_half_mirror row_mask:0xf bank_mask:0xf
	v_and_b32_e32 v193, 0xffff0000, v24
	v_lshlrev_b32_e32 v194, 16, v25
	v_add_f32_dpp v148, v148, v148 row_mirror row_mask:0xf bank_mask:0xf
	v_and_b32_e32 v195, 0xffff0000, v25
	v_mul_f32_e32 v34, v164, v188
	v_add_f32_dpp v148, v148, v148 row_bcast:15 row_mask:0xa bank_mask:0xf
	v_mul_f32_e32 v35, v165, v189
	v_mul_f32_e32 v36, v166, v190
	v_add_f32_dpp v148, v148, v148 row_bcast:31 row_mask:0xc bank_mask:0xf
	v_mul_f32_e32 v37, v167, v191
	v_mul_f32_e32 v38, v168, v192
	v_readlane_b32 s0, v148, 63
	v_mul_f32_e32 v39, v169, v193
	v_mul_f32_e32 v40, v170, v194
	v_mov_b32_e32 v148, s0
	v_mul_f32_e32 v41, v171, v195
	v_fmac_f32_e32 v34, v172, v204
	v_fmamk_f32 v148, v148, 0x3b000000, v162
	v_fmac_f32_e32 v35, v173, v205
	v_fmac_f32_e32 v36, v174, v206
	v_mul_f32_e32 v43, 0x4b800000, v148
	v_fmac_f32_e32 v37, v175, v207
	v_fmac_f32_e32 v38, v176, v208
	v_cmp_gt_f32_e32 vcc, s31, v148
	v_fmac_f32_e32 v39, v177, v209
	v_fmac_f32_e32 v40, v178, v210
	v_cndmask_b32_e32 v148, v148, v43, vcc
	v_fmac_f32_e32 v41, v179, v211
	v_fmac_f32_e32 v34, v180, v196
	v_rsq_f32_e32 v148, v148
	v_fmac_f32_e32 v35, v181, v197
	v_fmac_f32_e32 v36, v182, v198
	v_mul_f32_e32 v43, 0x45800000, v148
	v_fmac_f32_e32 v37, v183, v199
	v_fmac_f32_e32 v38, v184, v200
	v_cndmask_b32_e32 v149, v148, v43, vcc
	v_fmac_f32_e32 v39, v185, v201
	v_fmac_f32_e32 v40, v186, v202
	v_mul_f32_e32 v140, v149, v140
	v_fmac_f32_e32 v41, v187, v203
	v_lshlrev_b32_e32 v150, 16, v6
	v_mul_f32_e32 v141, v149, v141
	v_and_b32_e32 v151, 0xffff0000, v6
	v_mul_f32_e32 v34, v150, v34
	v_mul_f32_e32 v142, v149, v142
	v_mul_f32_e32 v35, v151, v35
	v_lshlrev_b32_e32 v150, 16, v7
	v_mul_f32_e32 v143, v149, v143
	v_and_b32_e32 v151, 0xffff0000, v7
	v_mul_f32_e32 v36, v150, v36
	v_mul_f32_e32 v144, v149, v144
	v_mul_f32_e32 v37, v151, v37
	v_lshlrev_b32_e32 v150, 16, v8
	v_mul_f32_e32 v145, v149, v145
	v_and_b32_e32 v151, 0xffff0000, v8
	v_mul_f32_e32 v38, v150, v38
	v_mul_f32_e32 v146, v149, v146
	v_mul_f32_e32 v39, v151, v39
	v_lshlrev_b32_e32 v150, 16, v9
	v_mul_f32_e32 v147, v149, v147
	v_and_b32_e32 v151, 0xffff0000, v9
	v_mul_f32_e32 v40, v150, v40
	v_cvt_pk_bf16_f32 v140, v140, v141
	v_mul_f32_e32 v41, v151, v41
	v_mul_f32_e32 v42, v34, v34
	v_cvt_pk_bf16_f32 v141, v142, v143
	v_fmac_f32_e32 v42, v35, v35
	v_fmac_f32_e32 v42, v36, v36
	v_cvt_pk_bf16_f32 v142, v144, v145
	v_fmac_f32_e32 v42, v37, v37
	v_fmac_f32_e32 v42, v38, v38
	v_cvt_pk_bf16_f32 v143, v146, v147
	v_fmac_f32_e32 v42, v39, v39
	v_fmac_f32_e32 v42, v40, v40
	global_store_dwordx4 v[156:157], v[140:143], off
	v_fmac_f32_e32 v42, v41, v41
	v_mad_i64_i32 v[152:153], s[42:43], s41, v221, v[58:59]
	s_add_u32 s41, s41, 1
	global_load_dwordx4 v[6:9], v[152:153], off offset:1536
	global_load_dwordx4 v[22:25], v[152:153], off offset:2560
	s_nop 1
	v_add_f32_dpp v42, v42, v42 quad_perm:[1,0,3,2] row_mask:0xf bank_mask:0xf
	s_waitcnt vmcnt(9)
	v_lshlrev_b32_e32 v196, 16, v26
	v_and_b32_e32 v197, 0xffff0000, v26
	v_add_f32_dpp v42, v42, v42 quad_perm:[2,3,0,1] row_mask:0xf bank_mask:0xf
	v_lshlrev_b32_e32 v198, 16, v27
	v_and_b32_e32 v199, 0xffff0000, v27
	v_add_f32_dpp v42, v42, v42 row_half_mirror row_mask:0xf bank_mask:0xf
	v_lshlrev_b32_e32 v200, 16, v28
	v_and_b32_e32 v201, 0xffff0000, v28
	v_add_f32_dpp v42, v42, v42 row_mirror row_mask:0xf bank_mask:0xf
	v_lshlrev_b32_e32 v202, 16, v29
	v_and_b32_e32 v203, 0xffff0000, v29
	v_add_f32_dpp v42, v42, v42 row_bcast:15 row_mask:0xa bank_mask:0xf
	v_mul_f32_e32 v140, v164, v196
	v_mul_f32_e32 v141, v165, v197
	v_add_f32_dpp v42, v42, v42 row_bcast:31 row_mask:0xc bank_mask:0xf
	v_mul_f32_e32 v142, v166, v198
	v_mul_f32_e32 v143, v167, v199
	v_readlane_b32 s0, v42, 63
	v_mul_f32_e32 v144, v168, v200
	v_mul_f32_e32 v145, v169, v201
	v_mov_b32_e32 v42, s0
	v_mul_f32_e32 v146, v170, v202
	v_mul_f32_e32 v147, v171, v203
	v_fmamk_f32 v42, v42, 0x3b000000, v162
	v_fmac_f32_e32 v140, v172, v188
	v_fmac_f32_e32 v141, v173, v189
	v_mul_f32_e32 v43, 0x4b800000, v42
	v_fmac_f32_e32 v142, v174, v190
	v_fmac_f32_e32 v143, v175, v191
	v_cmp_gt_f32_e32 vcc, s31, v42
	v_fmac_f32_e32 v144, v176, v192
	v_fmac_f32_e32 v145, v177, v193
	v_cndmask_b32_e32 v42, v42, v43, vcc
	v_fmac_f32_e32 v146, v178, v194
	v_fmac_f32_e32 v147, v179, v195
	v_rsq_f32_e32 v42, v42
	v_fmac_f32_e32 v140, v180, v204
	v_fmac_f32_e32 v141, v181, v205
	v_mul_f32_e32 v43, 0x45800000, v42
	v_fmac_f32_e32 v142, v182, v206
	v_fmac_f32_e32 v143, v183, v207
	v_cndmask_b32_e32 v149, v42, v43, vcc
	v_fmac_f32_e32 v144, v184, v208
	v_fmac_f32_e32 v145, v185, v209
	v_mul_f32_e32 v34, v149, v34
	v_fmac_f32_e32 v146, v186, v210
	v_fmac_f32_e32 v147, v187, v211
	v_mul_f32_e32 v35, v149, v35
	v_lshlrev_b32_e32 v150, 16, v10
	v_and_b32_e32 v151, 0xffff0000, v10
	v_mul_f32_e32 v36, v149, v36
	v_mul_f32_e32 v140, v150, v140
	v_mul_f32_e32 v141, v151, v141
	v_mul_f32_e32 v37, v149, v37
	v_lshlrev_b32_e32 v150, 16, v11
	v_and_b32_e32 v151, 0xffff0000, v11
	v_mul_f32_e32 v38, v149, v38
	v_mul_f32_e32 v142, v150, v142
	v_mul_f32_e32 v143, v151, v143
	v_mul_f32_e32 v39, v149, v39
	v_lshlrev_b32_e32 v150, 16, v12
	v_and_b32_e32 v151, 0xffff0000, v12
	v_mul_f32_e32 v40, v149, v40
	v_mul_f32_e32 v144, v150, v144
	v_mul_f32_e32 v145, v151, v145
	v_mul_f32_e32 v41, v149, v41
	v_lshlrev_b32_e32 v150, 16, v13
	v_and_b32_e32 v151, 0xffff0000, v13
	v_cvt_pk_bf16_f32 v34, v34, v35
	v_mul_f32_e32 v146, v150, v146
	v_mul_f32_e32 v147, v151, v147
	v_cvt_pk_bf16_f32 v35, v36, v37
	v_mul_f32_e32 v148, v140, v140
	v_fmac_f32_e32 v148, v141, v141
	v_cvt_pk_bf16_f32 v36, v38, v39
	v_fmac_f32_e32 v148, v142, v142
	v_fmac_f32_e32 v148, v143, v143
	v_cvt_pk_bf16_f32 v37, v40, v41
	v_fmac_f32_e32 v148, v144, v144
	v_fmac_f32_e32 v148, v145, v145
	global_store_dwordx4 v[156:157], v[34:37], off offset:2048
	v_fmac_f32_e32 v148, v146, v146
	v_fmac_f32_e32 v148, v147, v147
	v_lshl_add_u64 v[156:157], v[156:157], 0, s[20:21]
	v_mad_i64_i32 v[152:153], s[42:43], s41, v221, v[58:59]
	s_add_u32 s41, s41, 1
	global_load_dwordx4 v[10:13], v[152:153], off offset:1536
	global_load_dwordx4 v[26:29], v[152:153], off offset:2560
	s_nop 1
	v_add_f32_dpp v148, v148, v148 quad_perm:[1,0,3,2] row_mask:0xf bank_mask:0xf
	s_waitcnt vmcnt(9)
; __device__ __forceinline__ unsigned cvt_pk_bf16(float lo, float hi) { unsigned r; asm volatile("v_cvt_pk_bf16_f32 %0, %1, %2" : "=v"(r) : "v"(lo), "v"(hi)); return r; }
; __device__ __forceinline__ float bf_lo(unsigned w) { return __uint_as_float(w << 16); }
; __device__ __forceinline__ float bf_hi(unsigned w) { return __uint_as_float(w & 0xffff0000u); }
; __global__ void __launch_bounds__(512, 2) trunk_fwd(Args args) {
;     ...
;                 for (int rr = 0; rr < 16; ++rr) {
;                     const int r = r0 + rr;
;                     const u32x4 gb = gb_n, gu = gu_n; const f32x4 pv4 = pv_n;
;                     if (rr < 15) { gb_n = *(const u32x4*)(Z + (size_t)(r + 1) * INP + 768 + c0); gu_n = *(const u32x4*)(Z + (size_t)(r + 1) * INP + 1280 + c0);
;                                    pv_n = *(const f32x4*)(pl + (size_t)(r + 1) * PLE + lane * 4); }
;                     float cv[8], uu[8]; float ss = 0.f;
; #pragma unroll
;                     for (int i = 0; i < 4; ++i) {
;                         uu[2 * i] = bf_lo(gu[i]); uu[2 * i + 1] = bf_hi(gu[i]);
;                         cv[2 * i] = bf_lo(gb[i]) * (w0[2 * i] * uu[2 * i] + w1[2 * i] * u1[2 * i] + w2[2 * i] * u2[2 * i]);
;                         cv[2 * i + 1] = bf_hi(gb[i]) * (w0[2 * i + 1] * uu[2 * i + 1] + w1[2 * i + 1] * u1[2 * i + 1] + w2[2 * i + 1] * u2[2 * i + 1]);
;                     }
; #pragma unroll
;                     for (int i = 0; i < 8; ++i) { ss += cv[i] * cv[i]; u2[i] = u1[i]; u1[i] = uu[i]; }
;                     ss = wave_sum(ss);
;                     const float rc = rsqrtf(ss * (1.0f / 512.0f) + EPS);
;                     u32x4 oc;
; #pragma unroll
;                     for (int i = 0; i < 4; ++i) oc[i] = cvt_pk_bf16(cv[2 * i] * rc, cv[2 * i + 1] * rc);
;                     *(u32x4*)(MIX + (size_t)r * 1024 + 512 + c0) = oc;
;                     u32x2 pw; pw.x = cvt_pk_bf16(pv4[0], pv4[1]); pw.y = cvt_pk_bf16(pv4[2], pv4[3]);
;                     *(u32x2*)(PB + (size_t)r * PLE + lane * 4) = pw;
;                 }
	v_lshlrev_b32_e32 v204, 16, v30
	v_and_b32_e32 v205, 0xffff0000, v30
	v_add_f32_dpp v148, v148, v148 quad_perm:[2,3,0,1] row_mask:0xf bank_mask:0xf
	v_lshlrev_b32_e32 v206, 16, v31
	v_and_b32_e32 v207, 0xffff0000, v31
	v_lshlrev_b32_e32 v208, 16, v32
	v_add_f32_dpp v148, v148, v148 row_half_mirror row_mask:0xf bank_mask:0xf
	v_and_b32_e32 v209, 0xffff0000, v32
	v_lshlrev_b32_e32 v210, 16, v33
	v_add_f32_dpp v148, v148, v148 row_mirror row_mask:0xf bank_mask:0xf
	v_and_b32_e32 v211, 0xffff0000, v33
	v_mul_f32_e32 v34, v164, v204
	v_add_f32_dpp v148, v148, v148 row_bcast:15 row_mask:0xa bank_mask:0xf
	v_mul_f32_e32 v35, v165, v205
	v_mul_f32_e32 v36, v166, v206
	v_add_f32_dpp v148, v148, v148 row_bcast:31 row_mask:0xc bank_mask:0xf
	v_mul_f32_e32 v37, v167, v207
	v_mul_f32_e32 v38, v168, v208
	v_readlane_b32 s0, v148, 63
	v_mul_f32_e32 v39, v169, v209
	v_mul_f32_e32 v40, v170, v210
	v_mov_b32_e32 v148, s0
	v_mul_f32_e32 v41, v171, v211
	v_fmac_f32_e32 v34, v172, v196
	v_fmamk_f32 v148, v148, 0x3b000000, v162
	v_fmac_f32_e32 v35, v173, v197
	v_fmac_f32_e32 v36, v174, v198
	v_mul_f32_e32 v43, 0x4b800000, v148
	v_fmac_f32_e32 v37, v175, v199
	v_fmac_f32_e32 v38, v176, v200
	v_cmp_gt_f32_e32 vcc, s31, v148
	v_fmac_f32_e32 v39, v177, v201
	v_fmac_f32_e32 v40, v178, v202
	v_cndmask_b32_e32 v148, v148, v43, vcc
	v_fmac_f32_e32 v41, v179, v203
	v_fmac_f32_e32 v34, v180, v188
	v_rsq_f32_e32 v148, v148
	v_fmac_f32_e32 v35, v181, v189
	v_fmac_f32_e32 v36, v182, v190
	v_mul_f32_e32 v43, 0x45800000, v148
	v_fmac_f32_e32 v37, v183, v191
	v_fmac_f32_e32 v38, v184, v192
	v_cndmask_b32_e32 v149, v148, v43, vcc
	v_fmac_f32_e32 v39, v185, v193
	v_fmac_f32_e32 v40, v186, v194
	v_mul_f32_e32 v140, v149, v140
	v_fmac_f32_e32 v41, v187, v195
	v_lshlrev_b32_e32 v150, 16, v14
	v_mul_f32_e32 v141, v149, v141
	v_and_b32_e32 v151, 0xffff0000, v14
	v_mul_f32_e32 v34, v150, v34
	v_mul_f32_e32 v142, v149, v142
	v_mul_f32_e32 v35, v151, v35
	v_lshlrev_b32_e32 v150, 16, v15
	v_mul_f32_e32 v143, v149, v143
	v_and_b32_e32 v151, 0xffff0000, v15
	v_mul_f32_e32 v36, v150, v36
	v_mul_f32_e32 v144, v149, v144
	v_mul_f32_e32 v37, v151, v37
	v_lshlrev_b32_e32 v150, 16, v16
	v_mul_f32_e32 v145, v149, v145
	v_and_b32_e32 v151, 0xffff0000, v16
	v_mul_f32_e32 v38, v150, v38
	v_mul_f32_e32 v146, v149, v146
	v_mul_f32_e32 v39, v151, v39
	v_lshlrev_b32_e32 v150, 16, v17
	v_mul_f32_e32 v147, v149, v147
	v_and_b32_e32 v151, 0xffff0000, v17
	v_mul_f32_e32 v40, v150, v40
	v_cvt_pk_bf16_f32 v140, v140, v141
	v_mul_f32_e32 v41, v151, v41
	v_mul_f32_e32 v42, v34, v34
	v_cvt_pk_bf16_f32 v141, v142, v143
	v_fmac_f32_e32 v42, v35, v35
	v_fmac_f32_e32 v42, v36, v36
	v_cvt_pk_bf16_f32 v142, v144, v145
	v_fmac_f32_e32 v42, v37, v37
	v_fmac_f32_e32 v42, v38, v38
	v_cvt_pk_bf16_f32 v143, v146, v147
	v_fmac_f32_e32 v42, v39, v39
	v_fmac_f32_e32 v42, v40, v40
	global_store_dwordx4 v[156:157], v[140:143], off
	v_fmac_f32_e32 v42, v41, v41
	v_mad_i64_i32 v[152:153], s[42:43], s41, v221, v[58:59]
	s_add_u32 s41, s41, 1
	global_load_dwordx4 v[14:17], v[152:153], off offset:1536
	global_load_dwordx4 v[30:33], v[152:153], off offset:2560
	s_nop 1
	v_add_f32_dpp v42, v42, v42 quad_perm:[1,0,3,2] row_mask:0xf bank_mask:0xf
	s_waitcnt vmcnt(9)
	v_lshlrev_b32_e32 v188, 16, v18
	s_nop 0
	v_add_f32_dpp v42, v42, v42 quad_perm:[2,3,0,1] row_mask:0xf bank_mask:0xf
	v_and_b32_e32 v189, 0xffff0000, v18
	v_lshlrev_b32_e32 v190, 16, v19
	v_add_f32_dpp v42, v42, v42 row_half_mirror row_mask:0xf bank_mask:0xf
	v_and_b32_e32 v191, 0xffff0000, v19
	v_lshlrev_b32_e32 v192, 16, v20
	v_add_f32_dpp v42, v42, v42 row_mirror row_mask:0xf bank_mask:0xf
	v_and_b32_e32 v193, 0xffff0000, v20
	v_lshlrev_b32_e32 v194, 16, v21
	v_add_f32_dpp v42, v42, v42 row_bcast:15 row_mask:0xa bank_mask:0xf
	v_and_b32_e32 v195, 0xffff0000, v21
	v_mul_f32_e32 v140, v164, v188
	v_add_f32_dpp v42, v42, v42 row_bcast:31 row_mask:0xc bank_mask:0xf
	v_mul_f32_e32 v141, v165, v189
	v_mul_f32_e32 v142, v166, v190
	v_readlane_b32 s0, v42, 63
	v_mul_f32_e32 v143, v167, v191
	v_mul_f32_e32 v144, v168, v192
	v_mov_b32_e32 v42, s0
	v_mul_f32_e32 v145, v169, v193
	v_mul_f32_e32 v146, v170, v194
	v_fmamk_f32 v42, v42, 0x3b000000, v162
	v_mul_f32_e32 v147, v171, v195
	v_fmac_f32_e32 v140, v172, v204
	v_mul_f32_e32 v43, 0x4b800000, v42
	v_fmac_f32_e32 v141, v173, v205
	v_fmac_f32_e32 v142, v174, v206
	v_cmp_gt_f32_e32 vcc, s31, v42
	v_fmac_f32_e32 v143, v175, v207
	v_fmac_f32_e32 v144, v176, v208
	v_cndmask_b32_e32 v42, v42, v43, vcc
	v_fmac_f32_e32 v145, v177, v209
	v_fmac_f32_e32 v146, v178, v210
	v_rsq_f32_e32 v42, v42
	v_fmac_f32_e32 v147, v179, v211
	v_fmac_f32_e32 v140, v180, v196
	v_mul_f32_e32 v43, 0x45800000, v42
	v_fmac_f32_e32 v141, v181, v197
	v_fmac_f32_e32 v142, v182, v198
	v_cndmask_b32_e32 v149, v42, v43, vcc
	v_fmac_f32_e32 v143, v183, v199
	v_fmac_f32_e32 v144, v184, v200
	v_mul_f32_e32 v34, v149, v34
	v_fmac_f32_e32 v145, v185, v201
	v_fmac_f32_e32 v146, v186, v202
	v_mul_f32_e32 v35, v149, v35
	v_fmac_f32_e32 v147, v187, v203
	v_lshlrev_b32_e32 v150, 16, v2
	v_mul_f32_e32 v36, v149, v36
	v_and_b32_e32 v151, 0xffff0000, v2
	v_mul_f32_e32 v140, v150, v140
	v_mul_f32_e32 v37, v149, v37
	v_mul_f32_e32 v141, v151, v141
	v_lshlrev_b32_e32 v150, 16, v3
	v_mul_f32_e32 v38, v149, v38
	v_and_b32_e32 v151, 0xffff0000, v3
	v_mul_f32_e32 v142, v150, v142
	v_mul_f32_e32 v39, v149, v39
	v_mul_f32_e32 v143, v151, v143
	v_lshlrev_b32_e32 v150, 16, v4
	v_mul_f32_e32 v40, v149, v40
	v_and_b32_e32 v151, 0xffff0000, v4
	v_mul_f32_e32 v144, v150, v144
	v_mul_f32_e32 v41, v149, v41
	v_mul_f32_e32 v145, v151, v145
	v_lshlrev_b32_e32 v150, 16, v5
	v_cvt_pk_bf16_f32 v34, v34, v35
	v_and_b32_e32 v151, 0xffff0000, v5
	v_mul_f32_e32 v146, v150, v146
	v_cvt_pk_bf16_f32 v35, v36, v37
	v_mul_f32_e32 v147, v151, v147
	v_mul_f32_e32 v148, v140, v140
	v_cvt_pk_bf16_f32 v36, v38, v39
	v_fmac_f32_e32 v148, v141, v141
	v_fmac_f32_e32 v148, v142, v142
	v_cvt_pk_bf16_f32 v37, v40, v41
	v_fmac_f32_e32 v148, v143, v143
	v_fmac_f32_e32 v148, v144, v144
	global_store_dwordx4 v[156:157], v[34:37], off offset:2048
	v_fmac_f32_e32 v148, v145, v145
	v_fmac_f32_e32 v148, v146, v146
	v_lshl_add_u64 v[156:157], v[156:157], 0, s[20:21]
	v_fmac_f32_e32 v148, v147, v147
	s_nop 1
	v_add_f32_dpp v148, v148, v148 quad_perm:[1,0,3,2] row_mask:0xf bank_mask:0xf
	s_waitcnt vmcnt(7)
; __device__ __forceinline__ unsigned cvt_pk_bf16(float lo, float hi) { unsigned r; asm volatile("v_cvt_pk_bf16_f32 %0, %1, %2" : "=v"(r) : "v"(lo), "v"(hi)); return r; }
; __device__ __forceinline__ float bf_lo(unsigned w) { return __uint_as_float(w << 16); }
; __device__ __forceinline__ float bf_hi(unsigned w) { return __uint_as_float(w & 0xffff0000u); }
; __global__ void __launch_bounds__(512, 2) trunk_fwd(Args args) {
;     ...
;                 for (int rr = 0; rr < 16; ++rr) {
;                     const int r = r0 + rr;
;                     const u32x4 gb = gb_n, gu = gu_n; const f32x4 pv4 = pv_n;
;                     if (rr < 15) { gb_n = *(const u32x4*)(Z + (size_t)(r + 1) * INP + 768 + c0); gu_n = *(const u32x4*)(Z + (size_t)(r + 1) * INP + 1280 + c0);
;                                    pv_n = *(const f32x4*)(pl + (size_t)(r + 1) * PLE + lane * 4); }
;                     float cv[8], uu[8]; float ss = 0.f;
; #pragma unroll
;                     for (int i = 0; i < 4; ++i) {
;                         uu[2 * i] = bf_lo(gu[i]); uu[2 * i + 1] = bf_hi(gu[i]);
;                         cv[2 * i] = bf_lo(gb[i]) * (w0[2 * i] * uu[2 * i] + w1[2 * i] * u1[2 * i] + w2[2 * i] * u2[2 * i]);
;                         cv[2 * i + 1] = bf_hi(gb[i]) * (w0[2 * i + 1] * uu[2 * i + 1] + w1[2 * i + 1] * u1[2 * i + 1] + w2[2 * i + 1] * u2[2 * i + 1]);
;                     }
; #pragma unroll
;                     for (int i = 0; i < 8; ++i) { ss += cv[i] * cv[i]; u2[i] = u1[i]; u1[i] = uu[i]; }
;                     ss = wave_sum(ss);
;                     const float rc = rsqrtf(ss * (1.0f / 512.0f) + EPS);
;                     u32x4 oc;
; #pragma unroll
;                     for (int i = 0; i < 4; ++i) oc[i] = cvt_pk_bf16(cv[2 * i] * rc, cv[2 * i + 1] * rc);
;                     *(u32x4*)(MIX + (size_t)r * 1024 + 512 + c0) = oc;
;                     u32x2 pw; pw.x = cvt_pk_bf16(pv4[0], pv4[1]); pw.y = cvt_pk_bf16(pv4[2], pv4[3]);
;                     *(u32x2*)(PB + (size_t)r * PLE + lane * 4) = pw;
;                 }
	v_lshlrev_b32_e32 v196, 16, v22
	v_and_b32_e32 v197, 0xffff0000, v22
	v_add_f32_dpp v148, v148, v148 quad_perm:[2,3,0,1] row_mask:0xf bank_mask:0xf
	v_lshlrev_b32_e32 v198, 16, v23
	v_and_b32_e32 v199, 0xffff0000, v23
	v_add_f32_dpp v148, v148, v148 row_half_mirror row_mask:0xf bank_mask:0xf
	v_lshlrev_b32_e32 v200, 16, v24
	v_and_b32_e32 v201, 0xffff0000, v24
	v_add_f32_dpp v148, v148, v148 row_mirror row_mask:0xf bank_mask:0xf
	v_lshlrev_b32_e32 v202, 16, v25
	v_and_b32_e32 v203, 0xffff0000, v25
	v_add_f32_dpp v148, v148, v148 row_bcast:15 row_mask:0xa bank_mask:0xf
	v_mul_f32_e32 v34, v164, v196
	v_mul_f32_e32 v35, v165, v197
	v_add_f32_dpp v148, v148, v148 row_bcast:31 row_mask:0xc bank_mask:0xf
	v_mul_f32_e32 v36, v166, v198
	v_mul_f32_e32 v37, v167, v199
	v_readlane_b32 s0, v148, 63
	v_mul_f32_e32 v38, v168, v200
	v_mul_f32_e32 v39, v169, v201
	v_mov_b32_e32 v148, s0
	v_mul_f32_e32 v40, v170, v202
	v_mul_f32_e32 v41, v171, v203
	v_fmamk_f32 v148, v148, 0x3b000000, v162
	v_fmac_f32_e32 v34, v172, v188
	v_fmac_f32_e32 v35, v173, v189
	v_mul_f32_e32 v43, 0x4b800000, v148
	v_fmac_f32_e32 v36, v174, v190
	v_fmac_f32_e32 v37, v175, v191
	v_cmp_gt_f32_e32 vcc, s31, v148
	v_fmac_f32_e32 v38, v176, v192
	v_fmac_f32_e32 v39, v177, v193
	v_cndmask_b32_e32 v148, v148, v43, vcc
	v_fmac_f32_e32 v40, v178, v194
	v_fmac_f32_e32 v41, v179, v195
	v_rsq_f32_e32 v148, v148
	v_fmac_f32_e32 v34, v180, v204
	v_fmac_f32_e32 v35, v181, v205
	v_mul_f32_e32 v43, 0x45800000, v148
	v_fmac_f32_e32 v36, v182, v206
	v_fmac_f32_e32 v37, v183, v207
	v_cndmask_b32_e32 v149, v148, v43, vcc
	v_fmac_f32_e32 v38, v184, v208
	v_fmac_f32_e32 v39, v185, v209
	v_mul_f32_e32 v140, v149, v140
	v_fmac_f32_e32 v40, v186, v210
	v_fmac_f32_e32 v41, v187, v211
	v_mul_f32_e32 v141, v149, v141
	v_lshlrev_b32_e32 v150, 16, v6
	v_and_b32_e32 v151, 0xffff0000, v6
	v_mul_f32_e32 v142, v149, v142
	v_mul_f32_e32 v34, v150, v34
	v_mul_f32_e32 v35, v151, v35
	v_mul_f32_e32 v143, v149, v143
	v_lshlrev_b32_e32 v150, 16, v7
	v_and_b32_e32 v151, 0xffff0000, v7
	v_mul_f32_e32 v144, v149, v144
	v_mul_f32_e32 v36, v150, v36
	v_mul_f32_e32 v37, v151, v37
	v_mul_f32_e32 v145, v149, v145
	v_lshlrev_b32_e32 v150, 16, v8
	v_and_b32_e32 v151, 0xffff0000, v8
	v_mul_f32_e32 v146, v149, v146
	v_mul_f32_e32 v38, v150, v38
	v_mul_f32_e32 v39, v151, v39
	v_mul_f32_e32 v147, v149, v147
	v_lshlrev_b32_e32 v150, 16, v9
	v_and_b32_e32 v151, 0xffff0000, v9
	v_cvt_pk_bf16_f32 v140, v140, v141
	v_mul_f32_e32 v40, v150, v40
	v_mul_f32_e32 v41, v151, v41
	v_cvt_pk_bf16_f32 v141, v142, v143
	v_mul_f32_e32 v42, v34, v34
	v_fmac_f32_e32 v42, v35, v35
	v_cvt_pk_bf16_f32 v142, v144, v145
	v_fmac_f32_e32 v42, v36, v36
	v_fmac_f32_e32 v42, v37, v37
	v_cvt_pk_bf16_f32 v143, v146, v147
	v_fmac_f32_e32 v42, v38, v38
	v_fmac_f32_e32 v42, v39, v39
	global_store_dwordx4 v[156:157], v[140:143], off
	v_fmac_f32_e32 v42, v40, v40
	v_fmac_f32_e32 v42, v41, v41
	s_nop 1
	v_add_f32_dpp v42, v42, v42 quad_perm:[1,0,3,2] row_mask:0xf bank_mask:0xf
	s_waitcnt vmcnt(5)
	v_lshlrev_b32_e32 v204, 16, v26
	s_nop 0
	v_add_f32_dpp v42, v42, v42 quad_perm:[2,3,0,1] row_mask:0xf bank_mask:0xf
	v_and_b32_e32 v205, 0xffff0000, v26
	v_lshlrev_b32_e32 v206, 16, v27
	v_add_f32_dpp v42, v42, v42 row_half_mirror row_mask:0xf bank_mask:0xf
	v_and_b32_e32 v207, 0xffff0000, v27
	v_lshlrev_b32_e32 v208, 16, v28
	v_add_f32_dpp v42, v42, v42 row_mirror row_mask:0xf bank_mask:0xf
	v_and_b32_e32 v209, 0xffff0000, v28
	v_lshlrev_b32_e32 v210, 16, v29
	v_add_f32_dpp v42, v42, v42 row_bcast:15 row_mask:0xa bank_mask:0xf
	v_and_b32_e32 v211, 0xffff0000, v29
	v_mul_f32_e32 v140, v164, v204
	v_add_f32_dpp v42, v42, v42 row_bcast:31 row_mask:0xc bank_mask:0xf
	v_mul_f32_e32 v141, v165, v205
	v_mul_f32_e32 v142, v166, v206
	v_readlane_b32 s0, v42, 63
	v_mul_f32_e32 v143, v167, v207
	v_mul_f32_e32 v144, v168, v208
	v_mov_b32_e32 v42, s0
	v_mul_f32_e32 v145, v169, v209
	v_mul_f32_e32 v146, v170, v210
	v_fmamk_f32 v42, v42, 0x3b000000, v162
	v_mul_f32_e32 v147, v171, v211
	v_fmac_f32_e32 v140, v172, v196
	v_mul_f32_e32 v43, 0x4b800000, v42
	v_fmac_f32_e32 v141, v173, v197
	v_fmac_f32_e32 v142, v174, v198
	v_cmp_gt_f32_e32 vcc, s31, v42
	v_fmac_f32_e32 v143, v175, v199
	v_fmac_f32_e32 v144, v176, v200
	v_cndmask_b32_e32 v42, v42, v43, vcc
	v_fmac_f32_e32 v145, v177, v201
	v_fmac_f32_e32 v146, v178, v202
	v_rsq_f32_e32 v42, v42
	v_fmac_f32_e32 v147, v179, v203
	v_fmac_f32_e32 v140, v180, v188
	v_mul_f32_e32 v43, 0x45800000, v42
	v_fmac_f32_e32 v141, v181, v189
	v_fmac_f32_e32 v142, v182, v190
	v_cndmask_b32_e32 v149, v42, v43, vcc
	v_fmac_f32_e32 v143, v183, v191
	v_fmac_f32_e32 v144, v184, v192
	v_mul_f32_e32 v34, v149, v34
	v_fmac_f32_e32 v145, v185, v193
	v_fmac_f32_e32 v146, v186, v194
	v_mul_f32_e32 v35, v149, v35
	v_fmac_f32_e32 v147, v187, v195
	v_lshlrev_b32_e32 v150, 16, v10
	v_mul_f32_e32 v36, v149, v36
	v_and_b32_e32 v151, 0xffff0000, v10
	v_mul_f32_e32 v140, v150, v140
	v_mul_f32_e32 v37, v149, v37
	v_mul_f32_e32 v141, v151, v141
	v_lshlrev_b32_e32 v150, 16, v11
	v_mul_f32_e32 v38, v149, v38
	v_and_b32_e32 v151, 0xffff0000, v11
	v_mul_f32_e32 v142, v150, v142
	v_mul_f32_e32 v39, v149, v39
	v_mul_f32_e32 v143, v151, v143
	v_lshlrev_b32_e32 v150, 16, v12
	v_mul_f32_e32 v40, v149, v40
	v_and_b32_e32 v151, 0xffff0000, v12
	v_mul_f32_e32 v144, v150, v144
	v_mul_f32_e32 v41, v149, v41
	v_mul_f32_e32 v145, v151, v145
	v_lshlrev_b32_e32 v150, 16, v13
	v_cvt_pk_bf16_f32 v34, v34, v35
	v_and_b32_e32 v151, 0xffff0000, v13
	v_mul_f32_e32 v146, v150, v146
	v_cvt_pk_bf16_f32 v35, v36, v37
	v_mul_f32_e32 v147, v151, v147
	v_mul_f32_e32 v148, v140, v140
	v_cvt_pk_bf16_f32 v36, v38, v39
	v_fmac_f32_e32 v148, v141, v141
	v_fmac_f32_e32 v148, v142, v142
	v_cvt_pk_bf16_f32 v37, v40, v41
	v_fmac_f32_e32 v148, v143, v143
	v_fmac_f32_e32 v148, v144, v144
	global_store_dwordx4 v[156:157], v[34:37], off offset:2048
	v_fmac_f32_e32 v148, v145, v145
	v_fmac_f32_e32 v148, v146, v146
	v_lshl_add_u64 v[156:157], v[156:157], 0, s[20:21]
	v_fmac_f32_e32 v148, v147, v147
	s_nop 1
	v_add_f32_dpp v148, v148, v148 quad_perm:[1,0,3,2] row_mask:0xf bank_mask:0xf
	s_waitcnt vmcnt(3)
; __device__ __forceinline__ unsigned cvt_pk_bf16(float lo, float hi) { unsigned r; asm volatile("v_cvt_pk_bf16_f32 %0, %1, %2" : "=v"(r) : "v"(lo), "v"(hi)); return r; }
; __device__ __forceinline__ float bf_lo(unsigned w) { return __uint_as_float(w << 16); }
; __device__ __forceinline__ float bf_hi(unsigned w) { return __uint_as_float(w & 0xffff0000u); }
; __global__ void __launch_bounds__(512, 2) trunk_fwd(Args args) {
;     ...
;                 for (int rr = 0; rr < 16; ++rr) {
;                     const int r = r0 + rr;
;                     const u32x4 gb = gb_n, gu = gu_n; const f32x4 pv4 = pv_n;
;                     if (rr < 15) { gb_n = *(const u32x4*)(Z + (size_t)(r + 1) * INP + 768 + c0); gu_n = *(const u32x4*)(Z + (size_t)(r + 1) * INP + 1280 + c0);
;                                    pv_n = *(const f32x4*)(pl + (size_t)(r + 1) * PLE + lane * 4); }
;                     float cv[8], uu[8]; float ss = 0.f;
; #pragma unroll
;                     for (int i = 0; i < 4; ++i) {
;                         uu[2 * i] = bf_lo(gu[i]); uu[2 * i + 1] = bf_hi(gu[i]);
;                         cv[2 * i] = bf_lo(gb[i]) * (w0[2 * i] * uu[2 * i] + w1[2 * i] * u1[2 * i] + w2[2 * i] * u2[2 * i]);
;                         cv[2 * i + 1] = bf_hi(gb[i]) * (w0[2 * i + 1] * uu[2 * i + 1] + w1[2 * i + 1] * u1[2 * i + 1] + w2[2 * i + 1] * u2[2 * i + 1]);
;                     }
; #pragma unroll
;                     for (int i = 0; i < 8; ++i) { ss += cv[i] * cv[i]; u2[i] = u1[i]; u1[i] = uu[i]; }
;                     ss = wave_sum(ss);
;                     const float rc = rsqrtf(ss * (1.0f / 512.0f) + EPS);
;                     u32x4 oc;
; #pragma unroll
;                     for (int i = 0; i < 4; ++i) oc[i] = cvt_pk_bf16(cv[2 * i] * rc, cv[2 * i + 1] * rc);
;                     *(u32x4*)(MIX + (size_t)r * 1024 + 512 + c0) = oc;
;                     u32x2 pw; pw.x = cvt_pk_bf16(pv4[0], pv4[1]); pw.y = cvt_pk_bf16(pv4[2], pv4[3]);
;                     *(u32x2*)(PB + (size_t)r * PLE + lane * 4) = pw;
;                 }
	v_lshlrev_b32_e32 v188, 16, v30
	v_and_b32_e32 v189, 0xffff0000, v30
	v_add_f32_dpp v148, v148, v148 quad_perm:[2,3,0,1] row_mask:0xf bank_mask:0xf
	v_lshlrev_b32_e32 v190, 16, v31
	v_and_b32_e32 v191, 0xffff0000, v31
	v_add_f32_dpp v148, v148, v148 row_half_mirror row_mask:0xf bank_mask:0xf
	v_lshlrev_b32_e32 v192, 16, v32
	v_and_b32_e32 v193, 0xffff0000, v32
	v_add_f32_dpp v148, v148, v148 row_mirror row_mask:0xf bank_mask:0xf
	v_lshlrev_b32_e32 v194, 16, v33
	v_and_b32_e32 v195, 0xffff0000, v33
	v_add_f32_dpp v148, v148, v148 row_bcast:15 row_mask:0xa bank_mask:0xf
	v_mul_f32_e32 v34, v164, v188
	v_mul_f32_e32 v35, v165, v189
	v_add_f32_dpp v148, v148, v148 row_bcast:31 row_mask:0xc bank_mask:0xf
	v_mul_f32_e32 v36, v166, v190
	v_mul_f32_e32 v37, v167, v191
	v_readlane_b32 s0, v148, 63
	v_mul_f32_e32 v38, v168, v192
	v_mul_f32_e32 v39, v169, v193
	v_mov_b32_e32 v148, s0
	v_mul_f32_e32 v40, v170, v194
	v_mul_f32_e32 v41, v171, v195
	v_fmamk_f32 v148, v148, 0x3b000000, v162
	v_fmac_f32_e32 v34, v172, v204
	v_fmac_f32_e32 v35, v173, v205
	v_mul_f32_e32 v43, 0x4b800000, v148
	v_fmac_f32_e32 v36, v174, v206
	v_fmac_f32_e32 v37, v175, v207
	v_cmp_gt_f32_e32 vcc, s31, v148
	v_fmac_f32_e32 v38, v176, v208
	v_fmac_f32_e32 v39, v177, v209
	v_cndmask_b32_e32 v148, v148, v43, vcc
	v_fmac_f32_e32 v40, v178, v210
	v_fmac_f32_e32 v41, v179, v211
	v_rsq_f32_e32 v148, v148
	v_fmac_f32_e32 v34, v180, v196
	v_fmac_f32_e32 v35, v181, v197
	v_mul_f32_e32 v43, 0x45800000, v148
	v_fmac_f32_e32 v36, v182, v198
	v_fmac_f32_e32 v37, v183, v199
	v_cndmask_b32_e32 v149, v148, v43, vcc
	v_fmac_f32_e32 v38, v184, v200
	v_fmac_f32_e32 v39, v185, v201
	v_mul_f32_e32 v140, v149, v140
	v_fmac_f32_e32 v40, v186, v202
	v_fmac_f32_e32 v41, v187, v203
	v_mul_f32_e32 v141, v149, v141
	v_lshlrev_b32_e32 v150, 16, v14
	v_and_b32_e32 v151, 0xffff0000, v14
	v_mul_f32_e32 v142, v149, v142
	v_mul_f32_e32 v34, v150, v34
	v_mul_f32_e32 v35, v151, v35
	v_mul_f32_e32 v143, v149, v143
	v_lshlrev_b32_e32 v150, 16, v15
	v_and_b32_e32 v151, 0xffff0000, v15
	v_mul_f32_e32 v144, v149, v144
	v_mul_f32_e32 v36, v150, v36
	v_mul_f32_e32 v37, v151, v37
	v_mul_f32_e32 v145, v149, v145
	v_lshlrev_b32_e32 v150, 16, v16
	v_and_b32_e32 v151, 0xffff0000, v16
	v_mul_f32_e32 v146, v149, v146
	v_mul_f32_e32 v38, v150, v38
	v_mul_f32_e32 v39, v151, v39
	v_mul_f32_e32 v147, v149, v147
	v_lshlrev_b32_e32 v150, 16, v17
	v_and_b32_e32 v151, 0xffff0000, v17
	v_cvt_pk_bf16_f32 v140, v140, v141
	v_mul_f32_e32 v40, v150, v40
	v_mul_f32_e32 v41, v151, v41
	v_cvt_pk_bf16_f32 v141, v142, v143
	v_mul_f32_e32 v42, v34, v34
	v_fmac_f32_e32 v42, v35, v35
	v_cvt_pk_bf16_f32 v142, v144, v145
	v_fmac_f32_e32 v42, v36, v36
	v_fmac_f32_e32 v42, v37, v37
	v_cvt_pk_bf16_f32 v143, v146, v147
	v_fmac_f32_e32 v42, v38, v38
	v_fmac_f32_e32 v42, v39, v39
	global_store_dwordx4 v[156:157], v[140:143], off
	v_fmac_f32_e32 v42, v40, v40
	v_fmac_f32_e32 v42, v41, v41
	s_nop 1
	v_add_f32_dpp v42, v42, v42 quad_perm:[1,0,3,2] row_mask:0xf bank_mask:0xf
	s_nop 1
	v_add_f32_dpp v42, v42, v42 quad_perm:[2,3,0,1] row_mask:0xf bank_mask:0xf
	s_nop 1
	v_add_f32_dpp v42, v42, v42 row_half_mirror row_mask:0xf bank_mask:0xf
	s_nop 1
	v_add_f32_dpp v42, v42, v42 row_mirror row_mask:0xf bank_mask:0xf
	s_nop 1
	v_add_f32_dpp v42, v42, v42 row_bcast:15 row_mask:0xa bank_mask:0xf
	s_nop 1
	v_add_f32_dpp v42, v42, v42 row_bcast:31 row_mask:0xc bank_mask:0xf
	s_nop 0
	v_readlane_b32 s0, v42, 63
	s_nop 1
	v_mov_b32_e32 v42, s0
	v_fmamk_f32 v42, v42, 0x3b000000, v162
	v_mul_f32_e32 v43, 0x4b800000, v42
	v_cmp_gt_f32_e32 vcc, s31, v42
	s_nop 1
	v_cndmask_b32_e32 v42, v42, v43, vcc
	v_rsq_f32_e32 v42, v42
	s_nop 0
	v_mul_f32_e32 v43, 0x45800000, v42
	v_cndmask_b32_e32 v149, v42, v43, vcc
	v_mul_f32_e32 v34, v149, v34
	v_mul_f32_e32 v35, v149, v35
	v_mul_f32_e32 v36, v149, v36
	v_mul_f32_e32 v37, v149, v37
	v_mul_f32_e32 v38, v149, v38
	v_mul_f32_e32 v39, v149, v39
	v_mul_f32_e32 v40, v149, v40
	v_mul_f32_e32 v41, v149, v41
	v_cvt_pk_bf16_f32 v34, v34, v35
	v_cvt_pk_bf16_f32 v35, v36, v37
	v_cvt_pk_bf16_f32 v36, v38, v39
	v_cvt_pk_bf16_f32 v37, v40, v41
	global_store_dwordx4 v[156:157], v[34:37], off offset:2048
	v_lshl_add_u64 v[156:157], v[156:157], 0, s[20:21]
	s_nop 1
	s_branch .LBB0_1053
